# v35 + LRU pass-1: PRM parameter load overlapped with x-tile loads (one memory round trip less per unit)
# speedup vs baseline: 1.0064x; 1.0064x over previous
; #define GAS __attribute__((address_space(1)))
; #define LAS __attribute__((address_space(3)))
; template <class T_> __device__ __forceinline__ T_* as_global(T_* p) { return (T_*)(GAS T_*)p; }
; template <int PASS>
; __device__ __forceinline__ void lru_unit(const LruPtrs& args, LAS unsigned char* lds, int chunk, int bl, int g, int ck) {
;     ...
;     const int tid = tid_, lane = tid & 63, n = lane & 31, hi = lane >> 5; const int w = __builtin_amdgcn_readfirstlane(tid >> 6);
;     unsigned char* ws = args.ws; asm volatile("" : "+s"(ws)); ws = as_global(ws);
;     GAS bf16* Z = (GAS bf16*)(ws + WS_Z);
;     GAS float* AGG = (GAS float*)(ws + WS_AGG);
;     GAS v4u* stash = (GAS v4u*)(ws + WS_STASH) + ((size_t)((bl * 16 + g) * 32 + ck) * NWAVES + w) * 8 * 64 + lane;
;     LAS float* WAG = (LAS float*)(lds + RING_OFF);
;     LAS float* PART = (LAS float*)(lds + RING_OFF + 4096);
;     LAS float* CARW = (LAS float*)(lds + RING_OFF + 8192);
;     LAS float* PRM = (LAS float*)(lds + RING_OFF + 12288);
;     const int tl = ck * 256 + w * 32 + n;
;     const size_t zr = (size_t)bl * T + tl;
;     const int cb0 = g * 64 + 4 * hi;
;     float av[8][4], uv[8][4]; v4u gtile[4]; unsigned gagg[8];
;     if (PASS == 1) {
;         { const float* src = (w < 4) ? args.conv_w + w * D : (w == 4) ? args.conv_b : (w == 5) ? args.b_lru_r : (w == 6) ? args.b_lru_i : (const float*)(ws + WS_COEF);
;           PRM[w * 64 + lane] = ((const GAS float*)src)[g * 64 + lane]; }
;         LAS bf16* XT = (LAS bf16*)(lds + RING_OFF + 32768 + w * 4864);
;         {
;             const int tl0 = ck * 256 + w * 32;
;             v4u xv[5];
; #pragma unroll
;             for (int i = 0; i < 5; ++i) { const int idx = lane + 64 * i, r = idx >> 3, ch = idx & 7; const int ts = tl0 - 3 + r;
;                 xv[i] = (v4u){0u, 0u, 0u, 0u};
;                 if (r < 35 && ts >= 0) xv[i] = *(const GAS v4u*)(Z + ((size_t)bl * T + ts) * LDZ + ZC_AX + g * 64 + ch * 8); }
.LBB0_433:
	s_sub_i32 s49, s46, 32
	s_bfe_u32 s2, s49, 0x40005
	v_and_b32_e32 v86, 63, v24
	s_lshl_b32 s44, s2, 6
	v_or_b32_e32 v0, s44, v86
	v_lshlrev_b32_e32 v0, 2, v0
	global_load_dword v178, v0, s[4:5]
	s_and_b32 s45, s46, 31
	s_lshl_b32 s51, s48, 5
	s_and_b32 s47, s18, 0xffffffc0
	s_lshl_b32 s52, s45, 8
	s_lshr_b32 s46, s49, 9
	s_lshl_b32 s53, s47, 2
	s_add_i32 s51, s52, s51
	v_lshlrev_b32_e32 v0, 3, v24
	s_lshl_b32 s50, s46, 13
	s_add_i32 s53, s53, 0
	s_lshl_b32 s52, s2, 7
	s_add_i32 s51, s51, -3
	v_and_b32_e32 v26, 56, v0
	s_add_u32 s52, s42, s52
	v_bfe_u32 v25, v24, 3, 3
	v_lshlrev_b32_e32 v0, 1, v26
	v_lshl_add_u32 v179, v86, 2, s53
	s_addc_u32 s53, s43, 0
	s_mov_b64 s[4:5], 0x13c00000
	v_add_u32_e32 v3, s51, v25
	v_lshl_add_u64 v[4:5], s[52:53], 0, v[0:1]
	v_mov_b32_e32 v2, 0
	v_mov_b32_e32 v6, 0
	v_mov_b32_e32 v7, 0
	v_mov_b32_e32 v8, 0
	v_cmp_lt_i32_e32 vcc, -1, v3
	v_lshl_add_u64 v[22:23], v[4:5], 0, s[4:5]
	v_mov_b32_e32 v9, 0
	s_and_saveexec_b64 s[4:5], vcc
	s_cbranch_execz .LBB0_435
	v_add_u32_e32 v0, s50, v3
	v_lshlrev_b64 v[4:5], 11, v[0:1]
	v_lshl_add_u64 v[4:5], v[22:23], 0, v[4:5]
	global_load_dwordx4 v[6:9], v[4:5], off

; #define LAS __attribute__((address_space(3)))
; template <int PASS>
; __device__ __forceinline__ void lru_unit(const LruPtrs& args, LAS unsigned char* lds, int chunk, int bl, int g, int ck) {
;     ...
; #pragma unroll
;             for (int i = 0; i < 5; ++i) { const int idx = lane + 64 * i, r = idx >> 3, ch = idx & 7;
;                 if (r < 35) { *(LAS v2u*)(XT + r * 68 + ch * 8) = (v2u){xv[i].x, xv[i].y}; *(LAS v2u*)(XT + r * 68 + ch * 8 + 4) = (v2u){xv[i].z, xv[i].w}; } }
;         }
;         __syncthreads();
;         v2u xw[4][8];
; #pragma unroll
;         for (int k = 0; k < 4; ++k)
; #pragma unroll
;             for (int q = 0; q < 8; ++q) xw[k][q] = *(const LAS v2u*)(XT + (n + k) * 68 + 8 * q + 4 * hi);
;         float xc[8][4];
; #pragma unroll
;         for (int q = 0; q < 8; ++q) { const f32x4 bb = *(const LAS f32x4*)(PRM + 4 * 64 + 8 * q + 4 * hi);
; #pragma unroll
;             for (int p = 0; p < 4; ++p) xc[q][p] = bb[p]; }
; #pragma unroll
;         for (int k = 0; k < 4; ++k) {
; #pragma unroll
;             for (int q = 0; q < 8; ++q) { const f32x4 cw = *(const LAS f32x4*)(PRM + k * 64 + 8 * q + 4 * hi);
;                 xc[q][0] += cw[0] * pg8::bf_lo(xw[k][q].x); xc[q][1] += cw[1] * pg8::bf_hi(xw[k][q].x); xc[q][2] += cw[2] * pg8::bf_lo(xw[k][q].y); xc[q][3] += cw[3] * pg8::bf_hi(xw[k][q].y); }
.LBB0_443:
	s_or_b64 exec, exec, s[4:5]
	s_mul_i32 s4, s48, 0x1300
	s_add_i32 s50, s4, 0
	v_lshl_add_u32 v0, v26, 1, s50
	s_movk_i32 s4, 0x88
	v_mad_u32_u24 v22, v25, s4, v0
	v_add_u32_e32 v23, 0x8000, v22
	s_waitcnt vmcnt(0)
	ds_write_b32 v179, v178 offset:12288
	ds_write2_b64 v23, v[6:7], v[8:9] offset1:1
	v_add_u32_e32 v6, 0x8440, v22
	ds_write2_b64 v6, v[2:3], v[4:5] offset1:1
	v_add_u32_e32 v2, 0x8880, v22
	ds_write2_b64 v2, v[14:15], v[16:17] offset1:1
	v_add_u32_e32 v2, 0x8cc0, v22
	ds_write2_b64 v2, v[10:11], v[12:13] offset1:1
	s_and_saveexec_b64 s[4:5], vcc
	v_mul_u32_u24_e32 v2, 0x88, v27
	v_add3_u32 v0, v0, v2, s79
	ds_write2_b64 v0, v[18:19], v[20:21] offset1:1
	s_or_b64 exec, exec, s[4:5]
	v_lshrrev_b32_e32 v2, 3, v24
	v_and_b32_e32 v87, 31, v24
	v_and_b32_e32 v88, 4, v2
	v_lshlrev_b32_e32 v2, 1, v88
	v_mul_u32_u24_e32 v3, 0x88, v87
	v_add3_u32 v2, s50, v2, v3
	v_add_u32_e32 v10, 0x8000, v2
	v_lshl_add_u32 v89, v88, 2, 0
	s_waitcnt lgkmcnt(0)
	s_barrier
	ds_read2_b64 v[90:93], v10 offset1:2
	ds_read2_b64 v[82:85], v10 offset0:4 offset1:6
	ds_read2_b64 v[50:53], v10 offset0:8 offset1:10
	ds_read2_b64 v[2:5], v10 offset0:12 offset1:14
	ds_read2_b64 v[94:97], v10 offset0:17 offset1:19
	ds_read2_b64 v[98:101], v10 offset0:21 offset1:23
	ds_read2_b64 v[54:57], v10 offset0:25 offset1:27
	ds_read2_b64 v[6:9], v10 offset0:29 offset1:31
	ds_read2_b64 v[34:37], v10 offset0:34 offset1:36
	ds_read2_b64 v[26:29], v10 offset0:38 offset1:40
	ds_read2_b64 v[18:21], v10 offset0:42 offset1:44
	ds_read2_b64 v[66:69], v10 offset0:46 offset1:48
	ds_read2_b64 v[38:41], v10 offset0:51 offset1:53
	ds_read2_b64 v[30:33], v10 offset0:55 offset1:57
	ds_read2_b64 v[22:25], v10 offset0:59 offset1:61
	ds_read2_b64 v[70:73], v10 offset0:63 offset1:65
	ds_read_b128 v[102:105], v89 offset:13312
	ds_read_b128 v[106:109], v89 offset:13344
	ds_read_b128 v[110:113], v89 offset:13376
	ds_read_b128 v[114:117], v89 offset:13408
	ds_read_b128 v[74:77], v89 offset:13440
	ds_read_b128 v[58:61], v89 offset:13472
	ds_read_b128 v[42:45], v89 offset:13504
	ds_read_b128 v[10:13], v89 offset:13536
	ds_read_b128 v[118:121], v89 offset:12288
	ds_read_b128 v[122:125], v89 offset:12320
	ds_read_b128 v[126:129], v89 offset:12352
	ds_read_b128 v[130:133], v89 offset:12384
	ds_read_b128 v[78:81], v89 offset:12416
	ds_read_b128 v[62:65], v89 offset:12448
	ds_read_b128 v[46:49], v89 offset:12480
	ds_read_b128 v[14:17], v89 offset:12512
	ds_read_b128 v[134:137], v89 offset:12544
	s_waitcnt lgkmcnt(14)
	v_lshlrev_b32_e32 v143, 16, v94
	v_lshlrev_b32_e32 v142, 16, v90
	s_waitcnt lgkmcnt(8)
	v_mov_b32_e32 v144, v118
	ds_read_b128 v[138:141], v89 offset:12576
	s_waitcnt lgkmcnt(1)
	v_mov_b32_e32 v145, v134
	v_pk_mul_f32 v[142:143], v[144:145], v[142:143]
	v_mov_b32_e32 v134, v119
	v_add_f32_e32 v102, v102, v142
	v_add_f32_e32 v144, v102, v143
	v_and_b32_e32 v143, 0xffff0000, v94
	v_and_b32_e32 v142, 0xffff0000, v90
	v_pk_mul_f32 v[118:119], v[134:135], v[142:143]
	v_lshlrev_b32_e32 v102, 16, v91
	v_add_f32_e32 v90, v103, v118
	v_add_f32_e32 v134, v90, v119
	v_lshlrev_b32_e32 v103, 16, v95
	v_mov_b32_e32 v118, v120
	v_mov_b32_e32 v119, v136
	v_pk_mul_f32 v[102:103], v[118:119], v[102:103]
	v_and_b32_e32 v95, 0xffff0000, v95
	v_add_f32_e32 v90, v104, v102
	v_and_b32_e32 v94, 0xffff0000, v91
	v_mov_b32_e32 v136, v121
	v_add_f32_e32 v135, v90, v103
	v_pk_mul_f32 v[90:91], v[136:137], v[94:95]
	v_mov_b32_e32 v94, v122
	v_add_f32_e32 v90, v105, v90
	v_add_f32_e32 v136, v90, v91
	v_lshlrev_b32_e32 v91, 16, v96
	v_lshlrev_b32_e32 v90, 16, v92
	s_waitcnt lgkmcnt(0)
	v_mov_b32_e32 v95, v138
	v_pk_mul_f32 v[90:91], v[94:95], v[90:91]
	v_mov_b32_e32 v138, v123
	v_add_f32_e32 v90, v106, v90
	v_add_f32_e32 v122, v90, v91
	v_and_b32_e32 v91, 0xffff0000, v96
	v_and_b32_e32 v90, 0xffff0000, v92
	v_pk_mul_f32 v[90:91], v[138:139], v[90:91]
	v_mov_b32_e32 v94, v124
	v_add_f32_e32 v90, v107, v90
	v_add_f32_e32 v123, v90, v91
	v_lshlrev_b32_e32 v91, 16, v97
	v_lshlrev_b32_e32 v90, 16, v93
	v_mov_b32_e32 v95, v140
	v_pk_mul_f32 v[90:91], v[94:95], v[90:91]
	v_mov_b32_e32 v140, v125
	v_add_f32_e32 v90, v108, v90
	v_add_f32_e32 v108, v90, v91
	v_and_b32_e32 v91, 0xffff0000, v97
	v_and_b32_e32 v90, 0xffff0000, v93
	v_pk_mul_f32 v[90:91], v[140:141], v[90:91]
	v_lshlrev_b32_e32 v103, 16, v98
	v_add_f32_e32 v90, v109, v90
	v_add_f32_e32 v124, v90, v91
	ds_read_b128 v[90:93], v89 offset:12608
	ds_read_b128 v[94:97], v89 offset:12640
	v_lshlrev_b32_e32 v102, 16, v82
	v_mov_b32_e32 v104, v126
	s_and_b32 s4, s49, 0x1ffffe00
	s_waitcnt lgkmcnt(1)
	v_mov_b32_e32 v105, v90
	v_pk_mul_f32 v[102:103], v[104:105], v[102:103]
	s_lshl_b32 s5, s2, 5
	v_add_f32_e32 v90, v110, v102
	v_add_f32_e32 v125, v90, v103
	v_and_b32_e32 v103, 0xffff0000, v98
	v_and_b32_e32 v102, 0xffff0000, v82
	v_mov_b32_e32 v90, v127
	v_pk_mul_f32 v[90:91], v[90:91], v[102:103]
	v_mov_b32_e32 v102, v128
	v_add_f32_e32 v82, v111, v90
	v_add_f32_e32 v126, v82, v91
	v_lshlrev_b32_e32 v91, 16, v99
	v_lshlrev_b32_e32 v90, 16, v83
	v_mov_b32_e32 v103, v92
	v_pk_mul_f32 v[90:91], v[102:103], v[90:91]
	v_mov_b32_e32 v92, v129
	v_add_f32_e32 v82, v112, v90
	v_add_f32_e32 v127, v82, v91
	v_and_b32_e32 v91, 0xffff0000, v99
	v_and_b32_e32 v90, 0xffff0000, v83
	v_pk_mul_f32 v[82:83], v[92:93], v[90:91]
	v_mov_b32_e32 v90, v130
	v_add_f32_e32 v82, v113, v82
	v_add_f32_e32 v128, v82, v83
	v_lshlrev_b32_e32 v83, 16, v100
	v_lshlrev_b32_e32 v82, 16, v84
	s_waitcnt lgkmcnt(0)
; #define LAS __attribute__((address_space(3)))
; template <int PASS>
; __device__ __forceinline__ void lru_unit(const LruPtrs& args, LAS unsigned char* lds, int chunk, int bl, int g, int ck) {
;     ...
;         for (int k = 0; k < 4; ++k) {
; #pragma unroll
;             for (int q = 0; q < 8; ++q) { const f32x4 cw = *(const LAS f32x4*)(PRM + k * 64 + 8 * q + 4 * hi);
;                 xc[q][0] += cw[0] * pg8::bf_lo(xw[k][q].x); xc[q][1] += cw[1] * pg8::bf_hi(xw[k][q].x); xc[q][2] += cw[2] * pg8::bf_lo(xw[k][q].y); xc[q][3] += cw[3] * pg8::bf_hi(xw[k][q].y); }
	v_mov_b32_e32 v91, v94
	v_pk_mul_f32 v[82:83], v[90:91], v[82:83]
	v_mov_b32_e32 v94, v131
	v_add_f32_e32 v82, v114, v82
	v_add_f32_e32 v129, v82, v83
	v_and_b32_e32 v83, 0xffff0000, v100
	v_and_b32_e32 v82, 0xffff0000, v84
	v_pk_mul_f32 v[82:83], v[94:95], v[82:83]
	v_mov_b32_e32 v90, v132
	v_add_f32_e32 v82, v115, v82
	v_add_f32_e32 v130, v82, v83
	v_lshlrev_b32_e32 v83, 16, v101
	v_lshlrev_b32_e32 v82, 16, v85
	v_mov_b32_e32 v91, v96
	v_pk_mul_f32 v[82:83], v[90:91], v[82:83]
	v_mov_b32_e32 v96, v133
	v_add_f32_e32 v82, v116, v82
	v_add_f32_e32 v131, v82, v83
	v_and_b32_e32 v83, 0xffff0000, v101
	v_and_b32_e32 v82, 0xffff0000, v85
	v_pk_mul_f32 v[82:83], v[96:97], v[82:83]
	v_lshlrev_b32_e32 v91, 16, v54
	v_add_f32_e32 v82, v117, v82
	v_add_f32_e32 v117, v82, v83
	ds_read_b128 v[82:85], v89 offset:12672
	ds_read_b128 v[94:97], v89 offset:12704
	v_lshlrev_b32_e32 v90, 16, v50
	v_mov_b32_e32 v92, v78
	s_or_b32 s4, s5, s4
	s_waitcnt lgkmcnt(1)
	v_mov_b32_e32 v93, v82
	v_pk_mul_f32 v[90:91], v[92:93], v[90:91]
	v_mov_b32_e32 v82, v79
	v_add_f32_e32 v74, v74, v90
	v_add_f32_e32 v132, v74, v91
	v_and_b32_e32 v91, 0xffff0000, v54
	v_and_b32_e32 v90, 0xffff0000, v50
	v_pk_mul_f32 v[78:79], v[82:83], v[90:91]
	v_lshlrev_b32_e32 v74, 16, v51
	v_add_f32_e32 v50, v75, v78
	v_add_f32_e32 v133, v50, v79
	v_lshlrev_b32_e32 v75, 16, v55
	v_mov_b32_e32 v78, v80
	v_mov_b32_e32 v79, v84
	v_pk_mul_f32 v[74:75], v[78:79], v[74:75]
	v_and_b32_e32 v55, 0xffff0000, v55
	v_add_f32_e32 v50, v76, v74
	v_and_b32_e32 v54, 0xffff0000, v51
	v_mov_b32_e32 v84, v81
	v_add_f32_e32 v92, v50, v75
	v_pk_mul_f32 v[50:51], v[84:85], v[54:55]
	v_mov_b32_e32 v74, v62
	v_add_f32_e32 v50, v77, v50
	v_add_f32_e32 v54, v50, v51
	v_lshlrev_b32_e32 v51, 16, v56
	v_lshlrev_b32_e32 v50, 16, v52
	s_waitcnt lgkmcnt(0)
	v_mov_b32_e32 v75, v94
	v_pk_mul_f32 v[50:51], v[74:75], v[50:51]
	v_and_b32_e32 v75, 0xffff0000, v56
	v_and_b32_e32 v74, 0xffff0000, v52
	v_mov_b32_e32 v94, v63
	v_add_f32_e32 v50, v58, v50
	v_pk_mul_f32 v[62:63], v[94:95], v[74:75]
	v_add_f32_e32 v51, v50, v51
	v_add_f32_e32 v50, v59, v62
	v_add_f32_e32 v52, v50, v63
	v_lshlrev_b32_e32 v59, 16, v57
	v_lshlrev_b32_e32 v58, 16, v53
	v_mov_b32_e32 v62, v64
	v_mov_b32_e32 v63, v96
	v_and_b32_e32 v57, 0xffff0000, v57
	v_and_b32_e32 v56, 0xffff0000, v53
	v_mov_b32_e32 v96, v65
	v_pk_mul_f32 v[58:59], v[62:63], v[58:59]
	v_pk_mul_f32 v[56:57], v[96:97], v[56:57]
	v_add_f32_e32 v50, v60, v58
	v_add_f32_e32 v53, v61, v56
	v_add_f32_e32 v50, v50, v59
	v_add_f32_e32 v53, v53, v57
	ds_read_b128 v[56:59], v89 offset:12736
	ds_read_b128 v[74:77], v89 offset:12768
	v_lshlrev_b32_e32 v61, 16, v6
	v_lshlrev_b32_e32 v60, 16, v2
	v_mov_b32_e32 v62, v46
	s_waitcnt lgkmcnt(1)
	v_mov_b32_e32 v63, v56
	v_pk_mul_f32 v[60:61], v[62:63], v[60:61]
	v_mov_b32_e32 v56, v47
	v_add_f32_e32 v42, v42, v60
	v_add_f32_e32 v94, v42, v61
	v_and_b32_e32 v61, 0xffff0000, v6
	v_and_b32_e32 v60, 0xffff0000, v2
	v_pk_mul_f32 v[46:47], v[56:57], v[60:61]
	v_lshlrev_b32_e32 v42, 16, v3
	v_add_f32_e32 v2, v43, v46
	v_add_f32_e32 v93, v2, v47
	v_lshlrev_b32_e32 v43, 16, v7
	v_mov_b32_e32 v46, v48
	v_mov_b32_e32 v47, v58
	v_pk_mul_f32 v[42:43], v[46:47], v[42:43]
	v_and_b32_e32 v7, 0xffff0000, v7
	v_add_f32_e32 v2, v44, v42
	v_and_b32_e32 v6, 0xffff0000, v3
	v_mov_b32_e32 v58, v49
	v_add_f32_e32 v116, v2, v43
	v_pk_mul_f32 v[2:3], v[58:59], v[6:7]
	v_lshlrev_b32_e32 v7, 16, v38
	v_add_f32_e32 v2, v45, v2
	ds_read_b128 v[56:59], v89 offset:12800
	ds_read_b128 v[60:63], v89 offset:12832
	ds_read_b128 v[96:99], v89 offset:12864
	ds_read_b128 v[118:121], v89 offset:12896
	ds_read_b128 v[46:49], v89 offset:12928
	ds_read_b128 v[42:45], v89 offset:12960
	ds_read_b128 v[82:85], v89 offset:12992
	ds_read_b128 v[78:81], v89 offset:13024
	ds_read_b128 v[100:103], v89 offset:13056
	v_lshlrev_b32_e32 v6, 16, v34
	s_waitcnt lgkmcnt(8)
	v_mov_b32_e32 v64, v56
	v_mov_b32_e32 v56, v58
	ds_read_b128 v[104:107], v89 offset:13088
	s_waitcnt lgkmcnt(1)
	v_mov_b32_e32 v65, v100
	v_pk_mul_f32 v[6:7], v[64:65], v[6:7]
	v_mov_b32_e32 v100, v57
	v_add_f32_e32 v6, v144, v6
	v_add_f32_e32 v115, v6, v7
	v_and_b32_e32 v7, 0xffff0000, v38
	v_and_b32_e32 v6, 0xffff0000, v34
	v_pk_mul_f32 v[6:7], v[100:101], v[6:7]
	v_mov_b32_e32 v57, v102
	v_add_f32_e32 v6, v134, v6
	v_add_f32_e32 v114, v6, v7
	v_lshlrev_b32_e32 v7, 16, v39
	v_lshlrev_b32_e32 v6, 16, v35
	v_pk_mul_f32 v[6:7], v[56:57], v[6:7]
	v_mov_b32_e32 v102, v59
	v_add_f32_e32 v6, v135, v6
	v_add_f32_e32 v113, v6, v7
	v_and_b32_e32 v7, 0xffff0000, v39
	v_and_b32_e32 v6, 0xffff0000, v35
	v_pk_mul_f32 v[6:7], v[102:103], v[6:7]
	v_mov_b32_e32 v34, v60
	v_add_f32_e32 v6, v136, v6
	v_add_f32_e32 v112, v6, v7
	v_lshlrev_b32_e32 v7, 16, v40
	v_lshlrev_b32_e32 v6, 16, v36
	s_waitcnt lgkmcnt(0)
	v_mov_b32_e32 v35, v104
	v_pk_mul_f32 v[6:7], v[34:35], v[6:7]
	v_mov_b32_e32 v104, v61
	v_add_f32_e32 v6, v122, v6
	v_add_f32_e32 v111, v6, v7
	v_and_b32_e32 v7, 0xffff0000, v40
	v_and_b32_e32 v6, 0xffff0000, v36
	v_pk_mul_f32 v[6:7], v[104:105], v[6:7]
	v_mov_b32_e32 v34, v62
	v_add_f32_e32 v6, v123, v6
	v_add_f32_e32 v110, v6, v7
	v_lshlrev_b32_e32 v7, 16, v41
	v_lshlrev_b32_e32 v6, 16, v37
	v_mov_b32_e32 v35, v106
	v_pk_mul_f32 v[6:7], v[34:35], v[6:7]
	v_mov_b32_e32 v106, v63
	v_add_f32_e32 v6, v108, v6
	v_add_f32_e32 v109, v6, v7
	v_and_b32_e32 v6, 0xffff0000, v37
	ds_read_b128 v[34:37], v89 offset:13120
	v_and_b32_e32 v7, 0xffff0000, v41
	v_pk_mul_f32 v[6:7], v[106:107], v[6:7]
	v_mov_b32_e32 v56, v96
	v_add_f32_e32 v6, v124, v6
	v_add_f32_e32 v100, v6, v7
	v_lshlrev_b32_e32 v7, 16, v30
	v_lshlrev_b32_e32 v6, 16, v26
	ds_read_b128 v[38:41], v89 offset:13152
	s_waitcnt lgkmcnt(1)
; __device__ __forceinline__ unsigned cvt_pk_bf16(float lo, float hi) { unsigned r; asm volatile("v_cvt_pk_bf16_f32 %0, %1, %2" : "=v"(r) : "v"(lo), "v"(hi)); return r; }
; #define GAS __attribute__((address_space(1)))
; #define LAS __attribute__((address_space(3)))
; template <int PASS>
; __device__ __forceinline__ void lru_unit(const LruPtrs& args, LAS unsigned char* lds, int chunk, int bl, int g, int ck) {
;     ...
;         for (int k = 0; k < 4; ++k) {
; #pragma unroll
;             for (int q = 0; q < 8; ++q) { const f32x4 cw = *(const LAS f32x4*)(PRM + k * 64 + 8 * q + 4 * hi);
;                 xc[q][0] += cw[0] * pg8::bf_lo(xw[k][q].x); xc[q][1] += cw[1] * pg8::bf_hi(xw[k][q].x); xc[q][2] += cw[2] * pg8::bf_lo(xw[k][q].y); xc[q][3] += cw[3] * pg8::bf_hi(xw[k][q].y); }
;         }
;         f32x16 ar[2], ai_[2];
; #pragma unroll
;         for (int rb = 0; rb < 2; ++rb) { ar[rb] = f32x16{}; ai_[rb] = f32x16{}; }
;         const GAS bf16* wrf = (const GAS bf16*)(ws + WS_WRF) + (size_t)g * (2 * 2 * 4 * 64 * 8) + lane * 8;
; #pragma unroll
;         for (int ks = 0; ks < 4; ++ks) {
;             v4u bw; bw.x = pg8::cvt_pk_bf16(xc[2 * ks][0], xc[2 * ks][1]); bw.y = pg8::cvt_pk_bf16(xc[2 * ks][2], xc[2 * ks][3]); bw.z = pg8::cvt_pk_bf16(xc[2 * ks + 1][0], xc[2 * ks + 1][1]); bw.w = pg8::cvt_pk_bf16(xc[2 * ks + 1][2], xc[2 * ks + 1][3]);
;             const bf16x8 bfr = __builtin_bit_cast(bf16x8, bw);
; #pragma unroll
;             for (int rb = 0; rb < 2; ++rb) {
;                 const bf16x8 wr_ = __builtin_bit_cast(bf16x8, *(const GAS v4u*)(wrf + ((0 * 2 + rb) * 4 + ks) * 512));
;                 const bf16x8 wi_ = __builtin_bit_cast(bf16x8, *(const GAS v4u*)(wrf + ((1 * 2 + rb) * 4 + ks) * 512));
;                 ar[rb] = __builtin_amdgcn_mfma_f32_32x32x16_bf16(wr_, bfr, ar[rb], 0, 0, 0);
;                 ai_[rb] = __builtin_amdgcn_mfma_f32_32x32x16_bf16(wi_, bfr, ai_[rb], 0, 0, 0);
	v_mov_b32_e32 v57, v34
	v_pk_mul_f32 v[6:7], v[56:57], v[6:7]
	v_mov_b32_e32 v34, v97
	v_add_f32_e32 v6, v125, v6
	v_add_f32_e32 v106, v6, v7
	v_and_b32_e32 v7, 0xffff0000, v30
	v_and_b32_e32 v6, 0xffff0000, v26
	v_pk_mul_f32 v[6:7], v[34:35], v[6:7]
	v_mov_b32_e32 v34, v98
	v_add_f32_e32 v6, v126, v6
	v_add_f32_e32 v103, v6, v7
	v_lshlrev_b32_e32 v7, 16, v31
	v_lshlrev_b32_e32 v6, 16, v27
	v_mov_b32_e32 v35, v36
	v_pk_mul_f32 v[6:7], v[34:35], v[6:7]
	v_mov_b32_e32 v36, v99
	v_add_f32_e32 v6, v127, v6
	v_add_f32_e32 v102, v6, v7
	v_and_b32_e32 v7, 0xffff0000, v31
	v_and_b32_e32 v6, 0xffff0000, v27
	v_pk_mul_f32 v[6:7], v[36:37], v[6:7]
	v_mov_b32_e32 v26, v118
	v_add_f32_e32 v6, v128, v6
	v_add_f32_e32 v99, v6, v7
	v_lshlrev_b32_e32 v7, 16, v32
	v_lshlrev_b32_e32 v6, 16, v28
	s_waitcnt lgkmcnt(0)
	v_mov_b32_e32 v27, v38
	v_pk_mul_f32 v[6:7], v[26:27], v[6:7]
	v_mov_b32_e32 v38, v119
	v_add_f32_e32 v6, v129, v6
	v_add_f32_e32 v97, v6, v7
	v_and_b32_e32 v7, 0xffff0000, v32
	v_and_b32_e32 v6, 0xffff0000, v28
	v_pk_mul_f32 v[6:7], v[38:39], v[6:7]
	v_mov_b32_e32 v26, v120
	v_add_f32_e32 v6, v130, v6
	v_add_f32_e32 v96, v6, v7
	v_lshlrev_b32_e32 v7, 16, v33
	v_lshlrev_b32_e32 v6, 16, v29
	v_mov_b32_e32 v27, v40
	v_pk_mul_f32 v[6:7], v[26:27], v[6:7]
	v_mov_b32_e32 v40, v121
	v_add_f32_e32 v6, v131, v6
	v_add_f32_e32 v95, v6, v7
	v_and_b32_e32 v6, 0xffff0000, v29
	ds_read_b128 v[26:29], v89 offset:13184
	v_and_b32_e32 v7, 0xffff0000, v33
	v_pk_mul_f32 v[6:7], v[40:41], v[6:7]
	v_mov_b32_e32 v34, v46
	v_add_f32_e32 v6, v117, v6
	v_add_f32_e32 v90, v6, v7
	v_lshlrev_b32_e32 v7, 16, v22
	v_lshlrev_b32_e32 v6, 16, v18
	ds_read_b128 v[30:33], v89 offset:13216
	s_waitcnt lgkmcnt(1)
	v_mov_b32_e32 v35, v26
	v_pk_mul_f32 v[6:7], v[34:35], v[6:7]
	v_mov_b32_e32 v26, v47
	v_add_f32_e32 v6, v132, v6
	v_add_f32_e32 v91, v6, v7
	v_and_b32_e32 v7, 0xffff0000, v22
	v_and_b32_e32 v6, 0xffff0000, v18
	v_pk_mul_f32 v[6:7], v[26:27], v[6:7]
	v_mov_b32_e32 v26, v48
	v_add_f32_e32 v6, v133, v6
	v_add_f32_e32 v107, v6, v7
	v_lshlrev_b32_e32 v7, 16, v23
	v_lshlrev_b32_e32 v6, 16, v19
	v_mov_b32_e32 v27, v28
	v_pk_mul_f32 v[6:7], v[26:27], v[6:7]
	v_mov_b32_e32 v28, v49
	v_add_f32_e32 v6, v92, v6
	v_add_f32_e32 v108, v6, v7
	v_and_b32_e32 v7, 0xffff0000, v23
	v_and_b32_e32 v6, 0xffff0000, v19
	s_or_b32 s4, s4, s45
	v_pk_mul_f32 v[6:7], v[28:29], v[6:7]
	s_lshl_b32 s4, s4, 3
	s_ashr_i32 s5, s48, 31
	v_add_f32_e32 v6, v54, v6
	s_add_u32 s4, s48, s4
	v_add_f32_e32 v105, v6, v7
	v_lshlrev_b32_e32 v7, 16, v24
	v_lshlrev_b32_e32 v6, 16, v20
	v_mov_b32_e32 v18, v42
	s_waitcnt lgkmcnt(0)
	v_mov_b32_e32 v19, v30
	s_addc_u32 s5, s5, 0
	v_pk_mul_f32 v[6:7], v[18:19], v[6:7]
	s_lshl_b64 s[4:5], s[4:5], 13
	v_add_f32_e32 v6, v51, v6
	s_add_u32 s4, s42, s4
	v_add_f32_e32 v104, v6, v7
	v_and_b32_e32 v7, 0xffff0000, v24
	v_and_b32_e32 v6, 0xffff0000, v20
	v_mov_b32_e32 v30, v43
	s_addc_u32 s5, s43, s5
	s_lshl_b32 s2, s2, 14
	v_pk_mul_f32 v[6:7], v[30:31], v[6:7]
	s_add_u32 s48, s42, s2
	v_add_f32_e32 v6, v52, v6
	v_lshlrev_b32_e32 v0, 4, v86
	s_addc_u32 s49, s43, 0
	v_add_f32_e32 v101, v6, v7
	v_lshlrev_b32_e32 v7, 16, v25
	v_lshlrev_b32_e32 v6, 16, v21
	v_mov_b32_e32 v18, v44
	v_mov_b32_e32 v19, v32
	v_lshl_add_u64 v[38:39], s[48:49], 0, v[0:1]
	s_mov_b32 s2, 0x2501000
	v_pk_mul_f32 v[6:7], v[18:19], v[6:7]
	v_add_co_u32_e32 v166, vcc, s2, v38
	v_add_f32_e32 v6, v50, v6
	s_nop 0
	v_addc_co_u32_e32 v167, vcc, 0, v39, vcc
	v_add_f32_e32 v98, v6, v7
	v_and_b32_e32 v7, 0xffff0000, v25
	v_and_b32_e32 v6, 0xffff0000, v21
	v_mov_b32_e32 v32, v45
	ds_read_b128 v[118:121], v89 offset:13248
	ds_read_b128 v[122:125], v89 offset:13280
	v_cvt_pk_bf16_f32 v126, v115, v114
	v_cvt_pk_bf16_f32 v127, v113, v112
	v_cvt_pk_bf16_f32 v128, v111, v110
	v_cvt_pk_bf16_f32 v129, v109, v100
	global_load_dwordx4 v[34:37], v[166:167], off offset:-4096
	global_load_dwordx4 v[130:133], v[166:167], off
	v_pk_mul_f32 v[6:7], v[32:33], v[6:7]
	v_add_f32_e32 v117, v2, v3
	v_add_f32_e32 v6, v53, v6
	v_add_f32_e32 v92, v6, v7
	v_lshlrev_b32_e32 v3, 16, v8
	v_lshlrev_b32_e32 v2, 16, v4
	v_mov_b32_e32 v6, v14
	v_mov_b32_e32 v7, v74
	v_pk_mul_f32 v[2:3], v[6:7], v[2:3]
	s_mov_b32 s2, 0x2503000
	v_add_f32_e32 v2, v10, v2
	v_add_f32_e32 v174, v2, v3
	v_and_b32_e32 v3, 0xffff0000, v8
	v_and_b32_e32 v2, 0xffff0000, v4
	v_mov_b32_e32 v74, v15
	v_add_co_u32_e32 v168, vcc, s2, v38
	v_pk_mul_f32 v[2:3], v[74:75], v[2:3]
	v_lshlrev_b32_e32 v19, 16, v70
	v_lshlrev_b32_e32 v18, 16, v66
	v_mov_b32_e32 v20, v82
	s_waitcnt lgkmcnt(1)
	v_mov_b32_e32 v21, v118
	v_addc_co_u32_e32 v169, vcc, 0, v39, vcc
	v_add_f32_e32 v2, v11, v2
	v_pk_mul_f32 v[18:19], v[20:21], v[18:19]
	global_load_dwordx4 v[56:59], v[168:169], off offset:-4096
	global_load_dwordx4 v[26:29], v[168:169], off
	v_cvt_pk_bf16_f32 v134, v106, v103
	v_cvt_pk_bf16_f32 v135, v102, v99
	v_cvt_pk_bf16_f32 v136, v97, v96
	v_cvt_pk_bf16_f32 v137, v95, v90
	global_load_dwordx4 v[146:149], v[166:167], off offset:1024
	global_load_dwordx4 v[150:153], v[168:169], off offset:1024
	v_add_f32_e32 v175, v2, v3
	v_lshlrev_b32_e32 v3, 16, v9
	v_lshlrev_b32_e32 v2, 16, v5
	v_mov_b32_e32 v6, v16
	v_mov_b32_e32 v7, v76
	v_add_f32_e32 v18, v94, v18
	v_pk_mul_f32 v[2:3], v[6:7], v[2:3]
	v_add_f32_e32 v94, v18, v19
	v_and_b32_e32 v19, 0xffff0000, v70
	v_and_b32_e32 v18, 0xffff0000, v66
	v_mov_b32_e32 v118, v83
	v_add_f32_e32 v2, v12, v2
	v_pk_mul_f32 v[74:75], v[118:119], v[18:19]
	v_add_f32_e32 v176, v2, v3
	v_and_b32_e32 v3, 0xffff0000, v9
	v_and_b32_e32 v2, 0xffff0000, v5
	v_mov_b32_e32 v76, v17
	v_add_f32_e32 v66, v93, v74
	v_pk_mul_f32 v[2:3], v[76:77], v[2:3]
	v_add_f32_e32 v93, v66, v75
	v_lshlrev_b32_e32 v75, 16, v71
	v_lshlrev_b32_e32 v74, 16, v67
	v_mov_b32_e32 v76, v84
	v_mov_b32_e32 v77, v120
	s_mov_b32 s2, 0x2502000
	v_pk_mul_f32 v[74:75], v[76:77], v[74:75]
	s_mov_b64 s[48:49], 0x2500000
	v_add_co_u32_e32 v172, vcc, s2, v38
	v_add_f32_e32 v66, v116, v74
	v_and_b32_e32 v71, 0xffff0000, v71
	v_and_b32_e32 v70, 0xffff0000, v67
	v_mov_b32_e32 v120, v85
	v_lshl_add_u64 v[170:171], v[38:39], 0, s[48:49]
	v_addc_co_u32_e32 v173, vcc, 0, v39, vcc
	v_add_f32_e32 v83, v66, v75
	v_pk_mul_f32 v[66:67], v[120:121], v[70:71]
	global_load_dwordx4 v[138:141], v[170:171], off offset:1024
	global_load_dwordx4 v[142:145], v[172:173], off offset:1024
	v_cvt_pk_bf16_f32 v154, v91, v107
	v_cvt_pk_bf16_f32 v155, v108, v105
	v_cvt_pk_bf16_f32 v156, v104, v101
	v_cvt_pk_bf16_f32 v157, v98, v92
	v_add_f32_e32 v66, v117, v66
	global_load_dwordx4 v[116:119], v[166:167], off offset:2048
	v_add_f32_e32 v82, v66, v67
	v_lshlrev_b32_e32 v67, 16, v72
	v_lshlrev_b32_e32 v66, 16, v68
	v_mov_b32_e32 v70, v78
	s_waitcnt lgkmcnt(0)
; __device__ __forceinline__ unsigned cvt_pk_bf16(float lo, float hi) { unsigned r; asm volatile("v_cvt_pk_bf16_f32 %0, %1, %2" : "=v"(r) : "v"(lo), "v"(hi)); return r; }
; __device__ __forceinline__ float sigm(float x) { return __builtin_amdgcn_rcpf(1.f + __expf(-x)); }
; #define GAS __attribute__((address_space(1)))
; #define LAS __attribute__((address_space(3)))
; template <int PASS>
; __device__ __forceinline__ void lru_unit(const LruPtrs& args, LAS unsigned char* lds, int chunk, int bl, int g, int ck) {
;     ...
;         for (int ks = 0; ks < 4; ++ks) {
;             v4u bw; bw.x = pg8::cvt_pk_bf16(xc[2 * ks][0], xc[2 * ks][1]); bw.y = pg8::cvt_pk_bf16(xc[2 * ks][2], xc[2 * ks][3]); bw.z = pg8::cvt_pk_bf16(xc[2 * ks + 1][0], xc[2 * ks + 1][1]); bw.w = pg8::cvt_pk_bf16(xc[2 * ks + 1][2], xc[2 * ks + 1][3]);
;             const bf16x8 bfr = __builtin_bit_cast(bf16x8, bw);
; #pragma unroll
;             for (int rb = 0; rb < 2; ++rb) {
;                 const bf16x8 wr_ = __builtin_bit_cast(bf16x8, *(const GAS v4u*)(wrf + ((0 * 2 + rb) * 4 + ks) * 512));
;                 const bf16x8 wi_ = __builtin_bit_cast(bf16x8, *(const GAS v4u*)(wrf + ((1 * 2 + rb) * 4 + ks) * 512));
;                 ar[rb] = __builtin_amdgcn_mfma_f32_32x32x16_bf16(wr_, bfr, ar[rb], 0, 0, 0);
;                 ai_[rb] = __builtin_amdgcn_mfma_f32_32x32x16_bf16(wi_, bfr, ai_[rb], 0, 0, 0);
;             }
;         }
; #pragma unroll
;         for (int q = 0; q < 8; ++q) {
;             const f32x4 br = *(const LAS f32x4*)(PRM + 5 * 64 + 8 * q + 4 * hi), bi = *(const LAS f32x4*)(PRM + 6 * 64 + 8 * q + 4 * hi), cf = *(const LAS f32x4*)(PRM + 7 * 64 + 8 * q + 4 * hi);
; #pragma unroll
;             for (int p = 0; p < 4; ++p) { const int rb = q >> 2, r = (q & 3) * 4 + p;
;                 const float rr = pg8::sigm(ar[rb][r] + br[p]), ii = pg8::sigm(ai_[rb][r] + bi[p]);
;                 const float a0 = __builtin_amdgcn_exp2f(cf[p] * rr);
;                 av[q][p] = a0; uv[q][p] = __builtin_amdgcn_sqrtf(fmaxf(1.f - a0 * a0, 0.f)) * (ii * xc[q][p]); }
	v_mov_b32_e32 v71, v122
	v_pk_mul_f32 v[66:67], v[70:71], v[66:67]
	v_mov_b32_e32 v122, v79
	v_add_f32_e32 v66, v174, v66
	v_add_f32_e32 v77, v66, v67
	v_and_b32_e32 v67, 0xffff0000, v72
	v_and_b32_e32 v66, 0xffff0000, v68
	v_pk_mul_f32 v[66:67], v[122:123], v[66:67]
	global_load_dwordx4 v[120:123], v[168:169], off offset:2048
	global_load_dwordx4 v[158:161], v[170:171], off offset:2048
	global_load_dwordx4 v[162:165], v[172:173], off offset:2048
	v_add_f32_e32 v66, v175, v66
	v_add_f32_e32 v76, v66, v67
	v_lshlrev_b32_e32 v67, 16, v73
	v_lshlrev_b32_e32 v66, 16, v69
	v_mov_b32_e32 v70, v80
	v_mov_b32_e32 v71, v124
	v_pk_mul_f32 v[66:67], v[70:71], v[66:67]
	v_add_f32_e32 v2, v13, v2
	v_add_f32_e32 v66, v176, v66
	v_add_f32_e32 v74, v66, v67
	v_and_b32_e32 v67, 0xffff0000, v73
	v_and_b32_e32 v66, 0xffff0000, v69
	v_mov_b32_e32 v124, v81
	v_add_f32_e32 v177, v2, v3
	s_waitcnt vmcnt(10)
	v_mfma_f32_32x32x16_bf16 v[2:17], v[130:133], v[126:129], 0
	v_mul_f32_e64 v66, v124, v66
	v_mul_f32_e64 v67, v125, v67
	v_cvt_pk_bf16_f32 v78, v94, v93
	v_cvt_pk_bf16_f32 v79, v83, v82
	v_cvt_pk_bf16_f32 v80, v77, v76
	s_mov_b32 s2, 0x29c01000
	v_add_f32_e32 v66, v177, v66
	v_add_f32_e32 v75, v66, v67
	v_cvt_pk_bf16_f32 v81, v74, v75
	global_load_dwordx4 v[66:69], v[170:171], off offset:3072
	global_load_dwordx4 v[70:73], v[172:173], off offset:3072
	s_waitcnt vmcnt(9)
	v_mfma_f32_32x32x16_bf16 v[2:17], v[146:149], v[134:137], v[2:17]
	s_waitcnt vmcnt(5)
	v_mfma_f32_32x32x16_bf16 v[2:17], v[116:119], v[154:157], v[2:17]
	global_load_dwordx4 v[116:119], v[166:167], off offset:3072
	v_mfma_f32_32x32x16_bf16 v[18:33], v[26:29], v[126:129], 0
	v_mfma_f32_32x32x16_bf16 v[34:49], v[34:37], v[126:129], 0
	v_mfma_f32_32x32x16_bf16 v[18:33], v[150:153], v[134:137], v[18:33]
	v_mfma_f32_32x32x16_bf16 v[50:65], v[56:59], v[126:129], 0
	ds_read_b128 v[124:127], v89 offset:13568
	ds_read_b128 v[128:131], v89 offset:13600
	v_mfma_f32_32x32x16_bf16 v[34:49], v[138:141], v[134:137], v[34:49]
	s_waitcnt vmcnt(5)
	v_mfma_f32_32x32x16_bf16 v[18:33], v[120:123], v[154:157], v[18:33]
	global_load_dwordx4 v[120:123], v[168:169], off offset:3072
	v_mfma_f32_32x32x16_bf16 v[50:65], v[142:145], v[134:137], v[50:65]
	s_waitcnt vmcnt(5)
	v_mfma_f32_32x32x16_bf16 v[34:49], v[158:161], v[154:157], v[34:49]
	s_waitcnt vmcnt(4)
	v_mfma_f32_32x32x16_bf16 v[50:65], v[162:165], v[154:157], v[50:65]
	s_waitcnt vmcnt(3)
	v_mfma_f32_32x32x16_bf16 v[34:49], v[66:69], v[78:81], v[34:49]
	s_waitcnt vmcnt(2)
	v_mfma_f32_32x32x16_bf16 v[50:65], v[70:73], v[78:81], v[50:65]
	v_lshl_add_u64 v[72:73], s[4:5], 0, v[0:1]
	s_waitcnt lgkmcnt(1)
	s_nop 7
	v_add_f32_e32 v0, v34, v124
	v_mul_f32_e32 v0, 0xbfb8aa3b, v0
	v_exp_f32_e32 v0, v0
	v_add_f32_e32 v35, v35, v125
	v_mul_f32_e32 v35, 0xbfb8aa3b, v35
	v_exp_f32_e32 v35, v35
	s_waitcnt vmcnt(1)
	v_mfma_f32_32x32x16_bf16 v[2:17], v[116:119], v[78:81], v[2:17]
	ds_read_b128 v[116:119], v89 offset:13824
	ds_read_b128 v[132:135], v89 offset:14080
	v_add_f32_e32 v0, 1.0, v0
	v_rcp_f32_e32 v0, v0
	v_add_f32_e32 v35, 1.0, v35
	s_waitcnt lgkmcnt(1)
	v_add_f32_e32 v34, v50, v116
	v_mul_f32_e32 v34, 0xbfb8aa3b, v34
	s_waitcnt lgkmcnt(0)
	v_mul_f32_e32 v0, v132, v0
	v_exp_f32_e32 v34, v34
	v_exp_f32_e32 v66, v0
	v_rcp_f32_e32 v35, v35
	v_add_f32_e32 v50, v51, v117
	v_add_f32_e32 v0, 1.0, v34
	v_fma_f32 v34, -v66, v66, 1.0
	v_rcp_f32_e32 v0, v0
	v_max_f32_e32 v34, 0, v34
	v_mul_f32_e32 v50, 0xbfb8aa3b, v50
	v_mul_f32_e32 v35, v133, v35
	v_sqrt_f32_e32 v34, v34
	v_exp_f32_e32 v50, v50
	v_exp_f32_e32 v68, v35
	v_mul_f32_e32 v0, v115, v0
	v_mul_f32_e32 v67, v0, v34
	v_add_f32_e32 v0, 1.0, v50
	v_fma_f32 v34, -v68, v68, 1.0
	v_add_f32_e32 v35, v36, v126
	v_rcp_f32_e32 v0, v0
	v_mul_f32_e32 v35, 0xbfb8aa3b, v35
	v_max_f32_e32 v34, 0, v34
	v_exp_f32_e32 v35, v35
	v_sqrt_f32_e32 v36, v34
	v_mul_f32_e32 v0, v114, v0
	v_add_f32_e32 v38, v38, v128
	v_add_f32_e32 v34, 1.0, v35
	v_mul_f32_e32 v69, v0, v36
	v_add_f32_e32 v36, v37, v127
	v_rcp_f32_e32 v34, v34
	v_mul_f32_e32 v36, 0xbfb8aa3b, v36
	v_exp_f32_e32 v36, v36
	v_add_f32_e32 v35, v52, v118
	v_mul_f32_e32 v35, 0xbfb8aa3b, v35
	v_mul_f32_e32 v34, v134, v34
	v_exp_f32_e32 v35, v35
	v_exp_f32_e32 v34, v34
	v_add_f32_e32 v36, 1.0, v36
	v_rcp_f32_e32 v36, v36
	v_mul_f32_e32 v38, 0xbfb8aa3b, v38
	v_exp_f32_e32 v38, v38
	v_add_f32_e32 v0, 1.0, v35
	v_fma_f32 v35, -v34, v34, 1.0
	v_add_f32_e32 v37, v53, v119
	ds_read_b128 v[136:139], v89 offset:13856
	ds_read_b128 v[140:143], v89 offset:14112
	v_rcp_f32_e32 v0, v0
	v_max_f32_e32 v35, 0, v35
	v_mul_f32_e32 v37, 0xbfb8aa3b, v37
	v_mul_f32_e32 v36, v135, v36
	v_sqrt_f32_e32 v35, v35
	v_exp_f32_e32 v37, v37
	v_exp_f32_e32 v36, v36
	v_add_f32_e32 v38, 1.0, v38
	v_add_f32_e32 v39, v39, v129
	v_rcp_f32_e32 v38, v38
	v_mul_f32_e32 v39, 0xbfb8aa3b, v39
	v_exp_f32_e32 v39, v39
	v_mul_f32_e32 v0, v113, v0
	v_mul_f32_e32 v35, v0, v35
	v_add_f32_e32 v0, 1.0, v37
	v_fma_f32 v37, -v36, v36, 1.0
	s_waitcnt lgkmcnt(1)
	v_add_f32_e32 v50, v54, v136
	v_rcp_f32_e32 v0, v0
	v_max_f32_e32 v37, 0, v37
	v_mul_f32_e32 v50, 0xbfb8aa3b, v50
	s_waitcnt lgkmcnt(0)
	v_mul_f32_e32 v38, v140, v38
	v_sqrt_f32_e32 v37, v37
	v_exp_f32_e32 v51, v50
	v_exp_f32_e32 v50, v38
	v_add_f32_e32 v39, 1.0, v39
	v_rcp_f32_e32 v39, v39
	v_mul_f32_e32 v0, v112, v0
	v_mul_f32_e32 v37, v0, v37
	v_add_f32_e32 v0, 1.0, v51
	v_fma_f32 v38, -v50, v50, 1.0
	v_rcp_f32_e32 v0, v0
	v_max_f32_e32 v38, 0, v38
	v_add_f32_e32 v51, v55, v137
	v_mul_f32_e32 v39, v141, v39
	v_sqrt_f32_e32 v38, v38
	v_mul_f32_e32 v51, 0xbfb8aa3b, v51
	v_exp_f32_e32 v52, v39
	v_add_f32_e32 v39, v40, v130
	v_exp_f32_e32 v53, v51
	v_mul_f32_e32 v39, 0xbfb8aa3b, v39
	v_exp_f32_e32 v39, v39
	v_mul_f32_e32 v0, v111, v0
	v_mul_f32_e32 v51, v0, v38
	v_fma_f32 v38, -v52, v52, 1.0
	v_add_f32_e32 v0, 1.0, v53
	v_max_f32_e32 v38, 0, v38
	v_rcp_f32_e32 v0, v0
	v_sqrt_f32_e32 v40, v38
	v_add_f32_e32 v38, 1.0, v39
	v_rcp_f32_e32 v38, v38
	v_mul_f32_e32 v0, v110, v0
	v_add_f32_e32 v39, v56, v138
	v_mul_f32_e32 v39, 0xbfb8aa3b, v39
	v_mul_f32_e32 v38, v142, v38
	v_mul_f32_e32 v53, v0, v40
	v_add_f32_e32 v40, v41, v131
	s_waitcnt vmcnt(0)
; __device__ __forceinline__ float sigm(float x) { return __builtin_amdgcn_rcpf(1.f + __expf(-x)); }
; #define LAS __attribute__((address_space(3)))
; template <int PASS>
; __device__ __forceinline__ void lru_unit(const LruPtrs& args, LAS unsigned char* lds, int chunk, int bl, int g, int ck) {
;     ...
; #pragma unroll
;         for (int q = 0; q < 8; ++q) {
;             const f32x4 br = *(const LAS f32x4*)(PRM + 5 * 64 + 8 * q + 4 * hi), bi = *(const LAS f32x4*)(PRM + 6 * 64 + 8 * q + 4 * hi), cf = *(const LAS f32x4*)(PRM + 7 * 64 + 8 * q + 4 * hi);
; #pragma unroll
;             for (int p = 0; p < 4; ++p) { const int rb = q >> 2, r = (q & 3) * 4 + p;
;                 const float rr = pg8::sigm(ar[rb][r] + br[p]), ii = pg8::sigm(ai_[rb][r] + bi[p]);
;                 const float a0 = __builtin_amdgcn_exp2f(cf[p] * rr);
;                 av[q][p] = a0; uv[q][p] = __builtin_amdgcn_sqrtf(fmaxf(1.f - a0 * a0, 0.f)) * (ii * xc[q][p]); }
	v_mfma_f32_32x32x16_bf16 v[18:33], v[120:123], v[78:81], v[18:33]
	v_exp_f32_e32 v39, v39
	v_exp_f32_e32 v38, v38
	v_mul_f32_e32 v40, 0xbfb8aa3b, v40
	ds_read_b128 v[78:81], v89 offset:13632
	ds_read_b128 v[110:113], v89 offset:13664
	v_exp_f32_e32 v40, v40
	v_add_f32_e32 v0, 1.0, v39
	v_fma_f32 v39, -v38, v38, 1.0
	v_rcp_f32_e32 v0, v0
	v_max_f32_e32 v39, 0, v39
	v_add_f32_e32 v40, 1.0, v40
	s_waitcnt lgkmcnt(1)
	v_add_f32_e32 v42, v42, v78
	v_sqrt_f32_e32 v39, v39
	v_rcp_f32_e32 v40, v40
	v_mul_f32_e32 v42, 0xbfb8aa3b, v42
	v_exp_f32_e32 v42, v42
	v_mul_f32_e32 v0, v109, v0
	v_add_f32_e32 v41, v57, v139
	v_mul_f32_e32 v41, 0xbfb8aa3b, v41
	v_mul_f32_e32 v39, v0, v39
	v_mul_f32_e32 v0, v143, v40
	v_exp_f32_e32 v41, v41
	v_exp_f32_e32 v40, v0
	ds_read_b128 v[114:117], v89 offset:13888
	ds_read_b128 v[118:121], v89 offset:14144
	v_add_f32_e32 v42, 1.0, v42
	v_add_f32_e32 v43, v43, v79
	v_rcp_f32_e32 v42, v42
	v_mul_f32_e32 v43, 0xbfb8aa3b, v43
	v_exp_f32_e32 v43, v43
	v_add_f32_e32 v0, 1.0, v41
	v_fma_f32 v41, -v40, v40, 1.0
	s_waitcnt lgkmcnt(1)
	v_add_f32_e32 v54, v58, v114
	v_rcp_f32_e32 v0, v0
	v_max_f32_e32 v41, 0, v41
	v_mul_f32_e32 v54, 0xbfb8aa3b, v54
	s_waitcnt lgkmcnt(0)
	v_mul_f32_e32 v42, v118, v42
	v_sqrt_f32_e32 v41, v41
	v_exp_f32_e32 v55, v54
	v_exp_f32_e32 v54, v42
	v_add_f32_e32 v43, 1.0, v43
	v_rcp_f32_e32 v43, v43
	v_mul_f32_e32 v0, v100, v0
	v_mul_f32_e32 v41, v0, v41
	v_add_f32_e32 v0, 1.0, v55
	v_fma_f32 v42, -v54, v54, 1.0
	v_add_f32_e32 v55, v59, v115
	v_rcp_f32_e32 v0, v0
	v_max_f32_e32 v42, 0, v42
	v_mul_f32_e32 v55, 0xbfb8aa3b, v55
	v_mul_f32_e32 v43, v119, v43
	v_sqrt_f32_e32 v42, v42
	v_exp_f32_e32 v57, v55
	v_exp_f32_e32 v56, v43
	v_mul_f32_e32 v0, v106, v0
	v_mul_f32_e32 v55, v0, v42
	v_add_f32_e32 v0, 1.0, v57
	v_fma_f32 v42, -v56, v56, 1.0
	v_add_f32_e32 v43, v44, v80
	v_rcp_f32_e32 v0, v0
	v_mul_f32_e32 v43, 0xbfb8aa3b, v43
	v_max_f32_e32 v42, 0, v42
	v_exp_f32_e32 v43, v43
	v_sqrt_f32_e32 v44, v42
	v_mul_f32_e32 v0, v103, v0
	v_add_f32_e32 v46, v46, v110
	v_add_f32_e32 v42, 1.0, v43
	v_mul_f32_e32 v57, v0, v44
	v_add_f32_e32 v44, v45, v81
	v_rcp_f32_e32 v42, v42
	v_mul_f32_e32 v44, 0xbfb8aa3b, v44
	v_exp_f32_e32 v44, v44
	v_add_f32_e32 v43, v60, v116
	v_mul_f32_e32 v43, 0xbfb8aa3b, v43
	v_mul_f32_e32 v42, v120, v42
	v_exp_f32_e32 v43, v43
	v_exp_f32_e32 v42, v42
	v_add_f32_e32 v44, 1.0, v44
	v_rcp_f32_e32 v44, v44
	v_mul_f32_e32 v46, 0xbfb8aa3b, v46
	v_exp_f32_e32 v46, v46
	v_add_f32_e32 v0, 1.0, v43
	v_fma_f32 v43, -v42, v42, 1.0
	v_add_f32_e32 v45, v61, v117
	ds_read_b128 v[122:125], v89 offset:13920
	ds_read_b128 v[126:129], v89 offset:14176
	v_rcp_f32_e32 v0, v0
	v_max_f32_e32 v43, 0, v43
	v_mul_f32_e32 v45, 0xbfb8aa3b, v45
	v_mul_f32_e32 v44, v121, v44
	v_sqrt_f32_e32 v43, v43
	v_exp_f32_e32 v45, v45
	v_exp_f32_e32 v44, v44
	v_add_f32_e32 v46, 1.0, v46
	v_add_f32_e32 v47, v47, v111
	v_rcp_f32_e32 v46, v46
	v_mul_f32_e32 v47, 0xbfb8aa3b, v47
	v_exp_f32_e32 v47, v47
	v_mul_f32_e32 v0, v102, v0
	v_mul_f32_e32 v43, v0, v43
	v_add_f32_e32 v0, 1.0, v45
	v_fma_f32 v45, -v44, v44, 1.0
	s_waitcnt lgkmcnt(1)
	v_add_f32_e32 v58, v62, v122
	v_rcp_f32_e32 v0, v0
	v_max_f32_e32 v45, 0, v45
	v_mul_f32_e32 v58, 0xbfb8aa3b, v58
	s_waitcnt lgkmcnt(0)
	v_mul_f32_e32 v46, v126, v46
	v_sqrt_f32_e32 v45, v45
	v_exp_f32_e32 v59, v58
	v_exp_f32_e32 v58, v46
	v_add_f32_e32 v47, 1.0, v47
	v_rcp_f32_e32 v47, v47
	v_mul_f32_e32 v0, v99, v0
	v_mul_f32_e32 v45, v0, v45
	v_add_f32_e32 v0, 1.0, v59
	v_fma_f32 v46, -v58, v58, 1.0
	v_rcp_f32_e32 v0, v0
	v_max_f32_e32 v46, 0, v46
	v_add_f32_e32 v59, v63, v123
	v_mul_f32_e32 v47, v127, v47
	v_sqrt_f32_e32 v46, v46
	v_mul_f32_e32 v59, 0xbfb8aa3b, v59
	v_exp_f32_e32 v60, v47
	v_add_f32_e32 v47, v48, v112
	v_exp_f32_e32 v61, v59
	v_mul_f32_e32 v47, 0xbfb8aa3b, v47
	v_exp_f32_e32 v47, v47
	v_mul_f32_e32 v0, v97, v0
	v_mul_f32_e32 v59, v0, v46
	v_fma_f32 v46, -v60, v60, 1.0
	v_add_f32_e32 v0, 1.0, v61
	v_max_f32_e32 v46, 0, v46
	v_rcp_f32_e32 v0, v0
	v_sqrt_f32_e32 v48, v46
	v_add_f32_e32 v46, 1.0, v47
	v_rcp_f32_e32 v46, v46
	v_mul_f32_e32 v0, v96, v0
	v_add_f32_e32 v47, v64, v124
	v_mul_f32_e32 v47, 0xbfb8aa3b, v47
	v_mul_f32_e32 v46, v128, v46
	v_mul_f32_e32 v61, v0, v48
	v_add_f32_e32 v48, v49, v113
	v_exp_f32_e32 v47, v47
	v_exp_f32_e32 v46, v46
	v_mul_f32_e32 v48, 0xbfb8aa3b, v48
	ds_read_b128 v[78:81], v89 offset:13696
	ds_read_b128 v[110:113], v89 offset:13728
	v_exp_f32_e32 v48, v48
	v_add_f32_e32 v0, 1.0, v47
	v_fma_f32 v47, -v46, v46, 1.0
	v_rcp_f32_e32 v0, v0
	v_max_f32_e32 v47, 0, v47
	v_add_f32_e32 v48, 1.0, v48
	s_waitcnt lgkmcnt(1)
	v_add_f32_e32 v2, v2, v78
	v_sqrt_f32_e32 v47, v47
	v_rcp_f32_e32 v48, v48
	v_mul_f32_e32 v2, 0xbfb8aa3b, v2
	v_exp_f32_e32 v2, v2
	v_mul_f32_e32 v0, v95, v0
	v_add_f32_e32 v49, v65, v125
	v_mul_f32_e32 v49, 0xbfb8aa3b, v49
	v_mul_f32_e32 v47, v0, v47
	v_mul_f32_e32 v0, v129, v48
	v_exp_f32_e32 v49, v49
	v_exp_f32_e32 v48, v0
	ds_read_b128 v[114:117], v89 offset:13952
	ds_read_b128 v[118:121], v89 offset:14208
	v_add_f32_e32 v2, 1.0, v2
	v_add_f32_e32 v3, v3, v79
	v_rcp_f32_e32 v2, v2
	v_mul_f32_e32 v3, 0xbfb8aa3b, v3
	v_exp_f32_e32 v3, v3
	v_add_f32_e32 v0, 1.0, v49
	v_fma_f32 v49, -v48, v48, 1.0
	s_waitcnt lgkmcnt(1)
	v_add_f32_e32 v18, v18, v114
	v_rcp_f32_e32 v0, v0
	v_max_f32_e32 v49, 0, v49
	v_mul_f32_e32 v18, 0xbfb8aa3b, v18
	s_waitcnt lgkmcnt(0)
; __device__ __forceinline__ float sigm(float x) { return __builtin_amdgcn_rcpf(1.f + __expf(-x)); }
; #define LAS __attribute__((address_space(3)))
; template <int PASS>
; __device__ __forceinline__ void lru_unit(const LruPtrs& args, LAS unsigned char* lds, int chunk, int bl, int g, int ck) {
;     ...
; #pragma unroll
;         for (int q = 0; q < 8; ++q) {
;             const f32x4 br = *(const LAS f32x4*)(PRM + 5 * 64 + 8 * q + 4 * hi), bi = *(const LAS f32x4*)(PRM + 6 * 64 + 8 * q + 4 * hi), cf = *(const LAS f32x4*)(PRM + 7 * 64 + 8 * q + 4 * hi);
; #pragma unroll
;             for (int p = 0; p < 4; ++p) { const int rb = q >> 2, r = (q & 3) * 4 + p;
;                 const float rr = pg8::sigm(ar[rb][r] + br[p]), ii = pg8::sigm(ai_[rb][r] + bi[p]);
;                 const float a0 = __builtin_amdgcn_exp2f(cf[p] * rr);
;                 av[q][p] = a0; uv[q][p] = __builtin_amdgcn_sqrtf(fmaxf(1.f - a0 * a0, 0.f)) * (ii * xc[q][p]); }
;         }
	v_mul_f32_e32 v2, v118, v2
	v_sqrt_f32_e32 v49, v49
	v_exp_f32_e32 v18, v18
	v_exp_f32_e32 v62, v2
	v_add_f32_e32 v3, 1.0, v3
	v_rcp_f32_e32 v3, v3
	v_mul_f32_e32 v0, v90, v0
	v_mul_f32_e32 v49, v0, v49
	v_add_f32_e32 v0, 1.0, v18
	v_fma_f32 v2, -v62, v62, 1.0
	v_add_f32_e32 v18, v19, v115
	v_rcp_f32_e32 v0, v0
	v_max_f32_e32 v2, 0, v2
	v_mul_f32_e32 v18, 0xbfb8aa3b, v18
	v_mul_f32_e32 v3, v119, v3
	v_sqrt_f32_e32 v2, v2
	v_exp_f32_e32 v18, v18
	v_exp_f32_e32 v64, v3
	v_mul_f32_e32 v0, v91, v0
	v_mul_f32_e32 v63, v0, v2
	v_add_f32_e32 v0, 1.0, v18
	v_fma_f32 v2, -v64, v64, 1.0
	v_add_f32_e32 v3, v4, v80
	v_rcp_f32_e32 v0, v0
	v_mul_f32_e32 v3, 0xbfb8aa3b, v3
	v_max_f32_e32 v2, 0, v2
	v_exp_f32_e32 v3, v3
	v_sqrt_f32_e32 v4, v2
	v_mul_f32_e32 v0, v107, v0
	v_add_f32_e32 v6, v6, v110
	v_add_f32_e32 v2, 1.0, v3
	v_mul_f32_e32 v65, v0, v4
	v_add_f32_e32 v4, v5, v81
	v_rcp_f32_e32 v2, v2
	v_mul_f32_e32 v4, 0xbfb8aa3b, v4
	v_exp_f32_e32 v4, v4
	v_add_f32_e32 v3, v20, v116
	v_mul_f32_e32 v3, 0xbfb8aa3b, v3
	v_mul_f32_e32 v2, v120, v2
	v_exp_f32_e32 v3, v3
	v_exp_f32_e32 v2, v2
	v_add_f32_e32 v4, 1.0, v4
	v_rcp_f32_e32 v4, v4
	v_mul_f32_e32 v6, 0xbfb8aa3b, v6
	v_exp_f32_e32 v6, v6
	v_add_f32_e32 v0, 1.0, v3
	v_fma_f32 v3, -v2, v2, 1.0
	v_add_f32_e32 v5, v21, v117
	ds_read_b128 v[122:125], v89 offset:13984
	ds_read_b128 v[126:129], v89 offset:14240
	v_rcp_f32_e32 v0, v0
	v_max_f32_e32 v3, 0, v3
	v_mul_f32_e32 v5, 0xbfb8aa3b, v5
	v_mul_f32_e32 v4, v121, v4
	v_sqrt_f32_e32 v3, v3
	v_exp_f32_e32 v5, v5
	v_exp_f32_e32 v4, v4
	v_add_f32_e32 v6, 1.0, v6
	v_add_f32_e32 v7, v7, v111
	v_rcp_f32_e32 v6, v6
	v_mul_f32_e32 v7, 0xbfb8aa3b, v7
	v_exp_f32_e32 v7, v7
	v_mul_f32_e32 v0, v108, v0
	v_mul_f32_e32 v3, v0, v3
	v_add_f32_e32 v0, 1.0, v5
	v_fma_f32 v5, -v4, v4, 1.0
	s_waitcnt lgkmcnt(1)
	v_add_f32_e32 v18, v22, v122
	v_rcp_f32_e32 v0, v0
	v_max_f32_e32 v5, 0, v5
	v_mul_f32_e32 v18, 0xbfb8aa3b, v18
	s_waitcnt lgkmcnt(0)
	v_mul_f32_e32 v6, v126, v6
	v_sqrt_f32_e32 v5, v5
	v_exp_f32_e32 v19, v18
	v_exp_f32_e32 v18, v6
	v_add_f32_e32 v7, 1.0, v7
	v_rcp_f32_e32 v7, v7
	v_mul_f32_e32 v0, v105, v0
	v_mul_f32_e32 v5, v0, v5
	v_add_f32_e32 v0, 1.0, v19
	v_fma_f32 v6, -v18, v18, 1.0
	v_rcp_f32_e32 v0, v0
	v_max_f32_e32 v6, 0, v6
	v_add_f32_e32 v19, v23, v123
	v_mul_f32_e32 v7, v127, v7
	v_sqrt_f32_e32 v6, v6
	v_mul_f32_e32 v19, 0xbfb8aa3b, v19
	v_exp_f32_e32 v20, v7
	v_add_f32_e32 v7, v8, v112
	v_exp_f32_e32 v21, v19
	v_mul_f32_e32 v7, 0xbfb8aa3b, v7
	v_exp_f32_e32 v7, v7
	v_mul_f32_e32 v0, v104, v0
	v_mul_f32_e32 v19, v0, v6
	v_fma_f32 v6, -v20, v20, 1.0
	v_add_f32_e32 v0, 1.0, v21
	v_max_f32_e32 v6, 0, v6
	v_rcp_f32_e32 v0, v0
	v_sqrt_f32_e32 v8, v6
	v_add_f32_e32 v6, 1.0, v7
	v_add_f32_e32 v7, v24, v124
	v_rcp_f32_e32 v6, v6
	v_mul_f32_e32 v7, 0xbfb8aa3b, v7
	v_exp_f32_e32 v7, v7
	v_mul_f32_e32 v0, v101, v0
	v_mul_f32_e32 v6, v128, v6
	v_mul_f32_e32 v21, v0, v8
	v_add_f32_e32 v8, v9, v113
	v_exp_f32_e32 v6, v6
	v_add_f32_e32 v0, 1.0, v7
	v_mul_f32_e32 v8, 0xbfb8aa3b, v8
	ds_read_b128 v[78:81], v89 offset:13760
	v_rcp_f32_e32 v0, v0
	v_exp_f32_e32 v8, v8
	v_fma_f32 v7, -v6, v6, 1.0
	v_max_f32_e32 v7, 0, v7
	v_mul_f32_e32 v0, v98, v0
	v_add_f32_e32 v8, 1.0, v8
	ds_read_b128 v[96:99], v89 offset:13792
	s_waitcnt lgkmcnt(1)
	v_add_f32_e32 v10, v10, v78
	v_sqrt_f32_e32 v7, v7
	v_rcp_f32_e32 v8, v8
	v_mul_f32_e32 v10, 0xbfb8aa3b, v10
	v_exp_f32_e32 v10, v10
	v_add_f32_e32 v9, v25, v125
	v_mul_f32_e32 v9, 0xbfb8aa3b, v9
	v_mul_f32_e32 v7, v0, v7
	v_mul_f32_e32 v0, v129, v8
	v_exp_f32_e32 v9, v9
	v_exp_f32_e32 v8, v0
	ds_read_b128 v[100:103], v89 offset:14016
	ds_read_b128 v[104:107], v89 offset:14272
	v_add_f32_e32 v10, 1.0, v10
	v_add_f32_e32 v11, v11, v79
	v_rcp_f32_e32 v10, v10
	v_mul_f32_e32 v11, 0xbfb8aa3b, v11
	v_exp_f32_e32 v11, v11
	v_add_f32_e32 v0, 1.0, v9
	v_fma_f32 v9, -v8, v8, 1.0
	s_waitcnt lgkmcnt(1)
	v_add_f32_e32 v22, v26, v100
	v_rcp_f32_e32 v0, v0
	v_max_f32_e32 v9, 0, v9
	v_mul_f32_e32 v22, 0xbfb8aa3b, v22
	s_waitcnt lgkmcnt(0)
	v_mul_f32_e32 v10, v104, v10
	v_sqrt_f32_e32 v9, v9
	v_exp_f32_e32 v23, v22
	v_exp_f32_e32 v22, v10
	v_add_f32_e32 v11, 1.0, v11
	v_rcp_f32_e32 v11, v11
	v_mul_f32_e32 v0, v92, v0
	v_mul_f32_e32 v9, v0, v9
	v_add_f32_e32 v0, 1.0, v23
	v_fma_f32 v10, -v22, v22, 1.0
	v_add_f32_e32 v23, v27, v101
	v_rcp_f32_e32 v0, v0
	v_max_f32_e32 v10, 0, v10
	v_mul_f32_e32 v23, 0xbfb8aa3b, v23
	v_mul_f32_e32 v11, v105, v11
	v_sqrt_f32_e32 v10, v10
	v_exp_f32_e32 v25, v23
	v_exp_f32_e32 v24, v11
	v_mul_f32_e32 v0, v94, v0
	v_mul_f32_e32 v23, v0, v10
	v_add_f32_e32 v0, 1.0, v25
	v_fma_f32 v10, -v24, v24, 1.0
	v_add_f32_e32 v11, v12, v80
	v_rcp_f32_e32 v0, v0
	v_mul_f32_e32 v11, 0xbfb8aa3b, v11
	v_max_f32_e32 v10, 0, v10
	v_exp_f32_e32 v11, v11
	v_sqrt_f32_e32 v12, v10
	v_mul_f32_e32 v0, v93, v0
	v_add_f32_e32 v14, v14, v96
	v_add_f32_e32 v10, 1.0, v11
	v_mul_f32_e32 v25, v0, v12
	v_add_f32_e32 v12, v13, v81
	v_rcp_f32_e32 v10, v10
	v_mul_f32_e32 v12, 0xbfb8aa3b, v12
	v_exp_f32_e32 v12, v12
	v_add_f32_e32 v11, v28, v102
	v_mul_f32_e32 v11, 0xbfb8aa3b, v11
	v_mul_f32_e32 v10, v106, v10
	v_exp_f32_e32 v11, v11
	v_exp_f32_e32 v10, v10
	v_add_f32_e32 v12, 1.0, v12
	v_rcp_f32_e32 v12, v12
	v_mul_f32_e32 v14, 0xbfb8aa3b, v14
	v_exp_f32_e32 v14, v14
	v_add_f32_e32 v0, 1.0, v11
	v_fma_f32 v11, -v10, v10, 1.0
	v_add_f32_e32 v13, v29, v103
	ds_read_b128 v[108:111], v89 offset:14048
	ds_read_b128 v[112:115], v89 offset:14304
	v_rcp_f32_e32 v0, v0
	v_max_f32_e32 v11, 0, v11
	v_mul_f32_e32 v13, 0xbfb8aa3b, v13
	v_mul_f32_e32 v12, v107, v12
	v_sqrt_f32_e32 v11, v11
	v_exp_f32_e32 v13, v13
	v_exp_f32_e32 v12, v12
	v_add_f32_e32 v14, 1.0, v14
	v_rcp_f32_e32 v14, v14
	v_mul_f32_e32 v0, v83, v0
	v_mul_f32_e32 v11, v0, v11
	v_add_f32_e32 v0, 1.0, v13
	v_fma_f32 v13, -v12, v12, 1.0
	s_waitcnt lgkmcnt(1)
; __device__ __forceinline__ float sigm(float x) { return __builtin_amdgcn_rcpf(1.f + __expf(-x)); }
; #define LAS __attribute__((address_space(3)))
; template <int PASS>
; __device__ __forceinline__ void lru_unit(const LruPtrs& args, LAS unsigned char* lds, int chunk, int bl, int g, int ck) {
;     ...
; #pragma unroll
;         for (int q = 0; q < 8; ++q) {
;             const f32x4 br = *(const LAS f32x4*)(PRM + 5 * 64 + 8 * q + 4 * hi), bi = *(const LAS f32x4*)(PRM + 6 * 64 + 8 * q + 4 * hi), cf = *(const LAS f32x4*)(PRM + 7 * 64 + 8 * q + 4 * hi);
; #pragma unroll
;             for (int p = 0; p < 4; ++p) { const int rb = q >> 2, r = (q & 3) * 4 + p;
;                 const float rr = pg8::sigm(ar[rb][r] + br[p]), ii = pg8::sigm(ai_[rb][r] + bi[p]);
;                 const float a0 = __builtin_amdgcn_exp2f(cf[p] * rr);
;                 av[q][p] = a0; uv[q][p] = __builtin_amdgcn_sqrtf(fmaxf(1.f - a0 * a0, 0.f)) * (ii * xc[q][p]); }
;         }
;     ...
;     if (PASS == 1) {
; #pragma unroll
;     for (int q = 0; q < 8; ++q)
;         asm volatile("s_nop 1\n\t"
;             LRU_STEP("row_shr:1 row_mask:0xf bank_mask:0xf") LRU_STEP("row_shr:2 row_mask:0xf bank_mask:0xf") LRU_STEP("row_shr:4 row_mask:0xf bank_mask:0xf")
;             LRU_STEP("row_shr:8 row_mask:0xf bank_mask:0xf") LRU_STEP("row_bcast:15 row_mask:0xa bank_mask:0xf")
;             : "+v"(uv[q][0]), "+v"(av[q][0]), "+v"(uv[q][1]), "+v"(av[q][1]), "+v"(uv[q][2]), "+v"(av[q][2]), "+v"(uv[q][3]), "+v"(av[q][3]));
	v_add_f32_e32 v26, v30, v108
	v_rcp_f32_e32 v0, v0
	v_max_f32_e32 v13, 0, v13
	v_mul_f32_e32 v26, 0xbfb8aa3b, v26
	s_waitcnt lgkmcnt(0)
	v_mul_f32_e32 v14, v112, v14
	v_add_f32_e32 v15, v15, v97
	v_sqrt_f32_e32 v13, v13
	v_exp_f32_e32 v27, v26
	v_exp_f32_e32 v26, v14
	v_mul_f32_e32 v15, 0xbfb8aa3b, v15
	v_exp_f32_e32 v15, v15
	v_mul_f32_e32 v0, v82, v0
	v_mul_f32_e32 v13, v0, v13
	v_add_f32_e32 v0, 1.0, v27
	v_fma_f32 v14, -v26, v26, 1.0
	v_rcp_f32_e32 v0, v0
	v_max_f32_e32 v14, 0, v14
	v_add_f32_e32 v27, v31, v109
	v_add_f32_e32 v15, 1.0, v15
	v_sqrt_f32_e32 v14, v14
	v_mul_f32_e32 v27, 0xbfb8aa3b, v27
	v_rcp_f32_e32 v15, v15
	v_exp_f32_e32 v28, v27
	v_mul_f32_e32 v0, v77, v0
	v_mul_f32_e32 v27, v0, v14
	v_mul_f32_e32 v14, v113, v15
	v_add_f32_e32 v0, 1.0, v28
	v_exp_f32_e32 v28, v14
	v_add_f32_e32 v14, v16, v98
	v_mul_f32_e32 v14, 0xbfb8aa3b, v14
	v_rcp_f32_e32 v0, v0
	v_fma_f32 v15, -v28, v28, 1.0
	v_exp_f32_e32 v14, v14
	v_max_f32_e32 v15, 0, v15
	v_sqrt_f32_e32 v15, v15
	v_mul_f32_e32 v0, v76, v0
	v_add_f32_e32 v14, 1.0, v14
	v_rcp_f32_e32 v14, v14
	v_mul_f32_e32 v29, v0, v15
	v_add_f32_e32 v15, v17, v99
	v_mul_f32_e32 v15, 0xbfb8aa3b, v15
	v_exp_f32_e32 v15, v15
	v_add_f32_e32 v16, v32, v110
	v_mul_f32_e32 v16, 0xbfb8aa3b, v16
	v_mul_f32_e32 v14, v114, v14
	v_exp_f32_e32 v16, v16
	v_exp_f32_e32 v14, v14
	v_add_f32_e32 v15, 1.0, v15
	v_rcp_f32_e32 v15, v15
	v_add_f32_e32 v0, 1.0, v16
	v_fma_f32 v16, -v14, v14, 1.0
	v_max_f32_e32 v17, 0, v16
	v_add_f32_e32 v16, v33, v111
	v_mul_f32_e32 v16, 0xbfb8aa3b, v16
	v_mul_f32_e32 v15, v115, v15
	v_exp_f32_e32 v30, v16
	v_exp_f32_e32 v16, v15
	v_rcp_f32_e32 v0, v0
	v_sqrt_f32_e32 v15, v17
	v_add_f32_e32 v17, 1.0, v30
	v_fma_f32 v30, -v16, v16, 1.0
	v_rcp_f32_e32 v17, v17
	v_max_f32_e32 v30, 0, v30
	v_sqrt_f32_e32 v30, v30
	v_mul_f32_e32 v0, v74, v0
	s_mov_b64 s[4:5], 0x29c00000
	v_mul_f32_e32 v15, v0, v15
	v_mul_f32_e32 v0, v75, v17
	v_lshl_add_u64 v[70:71], v[72:73], 0, s[4:5]
	v_mul_f32_e32 v17, v0, v30
	v_add_co_u32_e32 v72, vcc, s2, v72
	s_nop 1
	v_fmac_f32_dpp v67, v67, v66 row_shr:1 row_mask:0xf bank_mask:0xf
	v_fmac_f32_dpp v69, v69, v68 row_shr:1 row_mask:0xf bank_mask:0xf
	v_fmac_f32_dpp v35, v35, v34 row_shr:1 row_mask:0xf bank_mask:0xf
	v_fmac_f32_dpp v37, v37, v36 row_shr:1 row_mask:0xf bank_mask:0xf
	v_mul_f32_dpp v66, v66, v66 row_shr:1 row_mask:0xf bank_mask:0xf
	v_mul_f32_dpp v68, v68, v68 row_shr:1 row_mask:0xf bank_mask:0xf
	v_mul_f32_dpp v34, v34, v34 row_shr:1 row_mask:0xf bank_mask:0xf
	v_mul_f32_dpp v36, v36, v36 row_shr:1 row_mask:0xf bank_mask:0xf
	v_fmac_f32_dpp v67, v67, v66 row_shr:2 row_mask:0xf bank_mask:0xf
	v_fmac_f32_dpp v69, v69, v68 row_shr:2 row_mask:0xf bank_mask:0xf
	v_fmac_f32_dpp v35, v35, v34 row_shr:2 row_mask:0xf bank_mask:0xf
	v_fmac_f32_dpp v37, v37, v36 row_shr:2 row_mask:0xf bank_mask:0xf
	v_mul_f32_dpp v66, v66, v66 row_shr:2 row_mask:0xf bank_mask:0xf
	v_mul_f32_dpp v68, v68, v68 row_shr:2 row_mask:0xf bank_mask:0xf
	v_mul_f32_dpp v34, v34, v34 row_shr:2 row_mask:0xf bank_mask:0xf
	v_mul_f32_dpp v36, v36, v36 row_shr:2 row_mask:0xf bank_mask:0xf
	v_fmac_f32_dpp v67, v67, v66 row_shr:4 row_mask:0xf bank_mask:0xf
	v_fmac_f32_dpp v69, v69, v68 row_shr:4 row_mask:0xf bank_mask:0xf
	v_fmac_f32_dpp v35, v35, v34 row_shr:4 row_mask:0xf bank_mask:0xf
	v_fmac_f32_dpp v37, v37, v36 row_shr:4 row_mask:0xf bank_mask:0xf
	v_mul_f32_dpp v66, v66, v66 row_shr:4 row_mask:0xf bank_mask:0xf
	v_mul_f32_dpp v68, v68, v68 row_shr:4 row_mask:0xf bank_mask:0xf
	v_mul_f32_dpp v34, v34, v34 row_shr:4 row_mask:0xf bank_mask:0xf
	v_mul_f32_dpp v36, v36, v36 row_shr:4 row_mask:0xf bank_mask:0xf
	v_fmac_f32_dpp v67, v67, v66 row_shr:8 row_mask:0xf bank_mask:0xf
	v_fmac_f32_dpp v69, v69, v68 row_shr:8 row_mask:0xf bank_mask:0xf
	v_fmac_f32_dpp v35, v35, v34 row_shr:8 row_mask:0xf bank_mask:0xf
	v_fmac_f32_dpp v37, v37, v36 row_shr:8 row_mask:0xf bank_mask:0xf
	v_mul_f32_dpp v66, v66, v66 row_shr:8 row_mask:0xf bank_mask:0xf
	v_mul_f32_dpp v68, v68, v68 row_shr:8 row_mask:0xf bank_mask:0xf
	v_mul_f32_dpp v34, v34, v34 row_shr:8 row_mask:0xf bank_mask:0xf
	v_mul_f32_dpp v36, v36, v36 row_shr:8 row_mask:0xf bank_mask:0xf
	v_fmac_f32_dpp v67, v67, v66 row_bcast:15 row_mask:0xa bank_mask:0xf
	v_fmac_f32_dpp v69, v69, v68 row_bcast:15 row_mask:0xa bank_mask:0xf
	v_fmac_f32_dpp v35, v35, v34 row_bcast:15 row_mask:0xa bank_mask:0xf
	v_fmac_f32_dpp v37, v37, v36 row_bcast:15 row_mask:0xa bank_mask:0xf
	v_mul_f32_dpp v66, v66, v66 row_bcast:15 row_mask:0xa bank_mask:0xf
	v_mul_f32_dpp v68, v68, v68 row_bcast:15 row_mask:0xa bank_mask:0xf
	v_mul_f32_dpp v34, v34, v34 row_bcast:15 row_mask:0xa bank_mask:0xf
	v_mul_f32_dpp v36, v36, v36 row_bcast:15 row_mask:0xa bank_mask:0xf

; template <int PASS>
; __device__ __forceinline__ void lru_unit(const LruPtrs& args, LAS unsigned char* lds, int chunk, int bl, int g, int ck) {
;     ...
;     if (PASS == 1) {
; #pragma unroll
;     for (int q = 0; q < 8; ++q)
;         asm volatile("s_nop 1\n\t"
;             LRU_STEP("row_shr:1 row_mask:0xf bank_mask:0xf") LRU_STEP("row_shr:2 row_mask:0xf bank_mask:0xf") LRU_STEP("row_shr:4 row_mask:0xf bank_mask:0xf")
;             LRU_STEP("row_shr:8 row_mask:0xf bank_mask:0xf") LRU_STEP("row_bcast:15 row_mask:0xa bank_mask:0xf")
;             : "+v"(uv[q][0]), "+v"(av[q][0]), "+v"(uv[q][1]), "+v"(av[q][1]), "+v"(uv[q][2]), "+v"(av[q][2]), "+v"(uv[q][3]), "+v"(av[q][3]));
	s_nop 1
	v_fmac_f32_dpp v51, v51, v50 row_shr:1 row_mask:0xf bank_mask:0xf
	v_fmac_f32_dpp v53, v53, v52 row_shr:1 row_mask:0xf bank_mask:0xf
	v_fmac_f32_dpp v39, v39, v38 row_shr:1 row_mask:0xf bank_mask:0xf
	v_fmac_f32_dpp v41, v41, v40 row_shr:1 row_mask:0xf bank_mask:0xf
	v_mul_f32_dpp v50, v50, v50 row_shr:1 row_mask:0xf bank_mask:0xf
	v_mul_f32_dpp v52, v52, v52 row_shr:1 row_mask:0xf bank_mask:0xf
	v_mul_f32_dpp v38, v38, v38 row_shr:1 row_mask:0xf bank_mask:0xf
	v_mul_f32_dpp v40, v40, v40 row_shr:1 row_mask:0xf bank_mask:0xf
	v_fmac_f32_dpp v51, v51, v50 row_shr:2 row_mask:0xf bank_mask:0xf
	v_fmac_f32_dpp v53, v53, v52 row_shr:2 row_mask:0xf bank_mask:0xf
	v_fmac_f32_dpp v39, v39, v38 row_shr:2 row_mask:0xf bank_mask:0xf
	v_fmac_f32_dpp v41, v41, v40 row_shr:2 row_mask:0xf bank_mask:0xf
	v_mul_f32_dpp v50, v50, v50 row_shr:2 row_mask:0xf bank_mask:0xf
	v_mul_f32_dpp v52, v52, v52 row_shr:2 row_mask:0xf bank_mask:0xf
	v_mul_f32_dpp v38, v38, v38 row_shr:2 row_mask:0xf bank_mask:0xf
	v_mul_f32_dpp v40, v40, v40 row_shr:2 row_mask:0xf bank_mask:0xf
	v_fmac_f32_dpp v51, v51, v50 row_shr:4 row_mask:0xf bank_mask:0xf
	v_fmac_f32_dpp v53, v53, v52 row_shr:4 row_mask:0xf bank_mask:0xf
	v_fmac_f32_dpp v39, v39, v38 row_shr:4 row_mask:0xf bank_mask:0xf
	v_fmac_f32_dpp v41, v41, v40 row_shr:4 row_mask:0xf bank_mask:0xf
	v_mul_f32_dpp v50, v50, v50 row_shr:4 row_mask:0xf bank_mask:0xf
	v_mul_f32_dpp v52, v52, v52 row_shr:4 row_mask:0xf bank_mask:0xf
	v_mul_f32_dpp v38, v38, v38 row_shr:4 row_mask:0xf bank_mask:0xf
	v_mul_f32_dpp v40, v40, v40 row_shr:4 row_mask:0xf bank_mask:0xf
	v_fmac_f32_dpp v51, v51, v50 row_shr:8 row_mask:0xf bank_mask:0xf
	v_fmac_f32_dpp v53, v53, v52 row_shr:8 row_mask:0xf bank_mask:0xf
	v_fmac_f32_dpp v39, v39, v38 row_shr:8 row_mask:0xf bank_mask:0xf
	v_fmac_f32_dpp v41, v41, v40 row_shr:8 row_mask:0xf bank_mask:0xf
	v_mul_f32_dpp v50, v50, v50 row_shr:8 row_mask:0xf bank_mask:0xf
	v_mul_f32_dpp v52, v52, v52 row_shr:8 row_mask:0xf bank_mask:0xf
	v_mul_f32_dpp v38, v38, v38 row_shr:8 row_mask:0xf bank_mask:0xf
	v_mul_f32_dpp v40, v40, v40 row_shr:8 row_mask:0xf bank_mask:0xf
	v_fmac_f32_dpp v51, v51, v50 row_bcast:15 row_mask:0xa bank_mask:0xf
	v_fmac_f32_dpp v53, v53, v52 row_bcast:15 row_mask:0xa bank_mask:0xf
	v_fmac_f32_dpp v39, v39, v38 row_bcast:15 row_mask:0xa bank_mask:0xf
	v_fmac_f32_dpp v41, v41, v40 row_bcast:15 row_mask:0xa bank_mask:0xf
	v_mul_f32_dpp v50, v50, v50 row_bcast:15 row_mask:0xa bank_mask:0xf
	v_mul_f32_dpp v52, v52, v52 row_bcast:15 row_mask:0xa bank_mask:0xf
	v_mul_f32_dpp v38, v38, v38 row_bcast:15 row_mask:0xa bank_mask:0xf
	v_mul_f32_dpp v40, v40, v40 row_bcast:15 row_mask:0xa bank_mask:0xf

; template <int PASS>
; __device__ __forceinline__ void lru_unit(const LruPtrs& args, LAS unsigned char* lds, int chunk, int bl, int g, int ck) {
;     ...
;     if (PASS == 1) {
; #pragma unroll
;     for (int q = 0; q < 8; ++q)
;         asm volatile("s_nop 1\n\t"
;             LRU_STEP("row_shr:1 row_mask:0xf bank_mask:0xf") LRU_STEP("row_shr:2 row_mask:0xf bank_mask:0xf") LRU_STEP("row_shr:4 row_mask:0xf bank_mask:0xf")
;             LRU_STEP("row_shr:8 row_mask:0xf bank_mask:0xf") LRU_STEP("row_bcast:15 row_mask:0xa bank_mask:0xf")
;             : "+v"(uv[q][0]), "+v"(av[q][0]), "+v"(uv[q][1]), "+v"(av[q][1]), "+v"(uv[q][2]), "+v"(av[q][2]), "+v"(uv[q][3]), "+v"(av[q][3]));
	s_nop 1
	v_fmac_f32_dpp v55, v55, v54 row_shr:1 row_mask:0xf bank_mask:0xf
	v_fmac_f32_dpp v57, v57, v56 row_shr:1 row_mask:0xf bank_mask:0xf
	v_fmac_f32_dpp v43, v43, v42 row_shr:1 row_mask:0xf bank_mask:0xf
	v_fmac_f32_dpp v45, v45, v44 row_shr:1 row_mask:0xf bank_mask:0xf
	v_mul_f32_dpp v54, v54, v54 row_shr:1 row_mask:0xf bank_mask:0xf
	v_mul_f32_dpp v56, v56, v56 row_shr:1 row_mask:0xf bank_mask:0xf
	v_mul_f32_dpp v42, v42, v42 row_shr:1 row_mask:0xf bank_mask:0xf
	v_mul_f32_dpp v44, v44, v44 row_shr:1 row_mask:0xf bank_mask:0xf
	v_fmac_f32_dpp v55, v55, v54 row_shr:2 row_mask:0xf bank_mask:0xf
	v_fmac_f32_dpp v57, v57, v56 row_shr:2 row_mask:0xf bank_mask:0xf
	v_fmac_f32_dpp v43, v43, v42 row_shr:2 row_mask:0xf bank_mask:0xf
	v_fmac_f32_dpp v45, v45, v44 row_shr:2 row_mask:0xf bank_mask:0xf
	v_mul_f32_dpp v54, v54, v54 row_shr:2 row_mask:0xf bank_mask:0xf
	v_mul_f32_dpp v56, v56, v56 row_shr:2 row_mask:0xf bank_mask:0xf
	v_mul_f32_dpp v42, v42, v42 row_shr:2 row_mask:0xf bank_mask:0xf
	v_mul_f32_dpp v44, v44, v44 row_shr:2 row_mask:0xf bank_mask:0xf
	v_fmac_f32_dpp v55, v55, v54 row_shr:4 row_mask:0xf bank_mask:0xf
	v_fmac_f32_dpp v57, v57, v56 row_shr:4 row_mask:0xf bank_mask:0xf
	v_fmac_f32_dpp v43, v43, v42 row_shr:4 row_mask:0xf bank_mask:0xf
	v_fmac_f32_dpp v45, v45, v44 row_shr:4 row_mask:0xf bank_mask:0xf
	v_mul_f32_dpp v54, v54, v54 row_shr:4 row_mask:0xf bank_mask:0xf
	v_mul_f32_dpp v56, v56, v56 row_shr:4 row_mask:0xf bank_mask:0xf
	v_mul_f32_dpp v42, v42, v42 row_shr:4 row_mask:0xf bank_mask:0xf
	v_mul_f32_dpp v44, v44, v44 row_shr:4 row_mask:0xf bank_mask:0xf
	v_fmac_f32_dpp v55, v55, v54 row_shr:8 row_mask:0xf bank_mask:0xf
	v_fmac_f32_dpp v57, v57, v56 row_shr:8 row_mask:0xf bank_mask:0xf
	v_fmac_f32_dpp v43, v43, v42 row_shr:8 row_mask:0xf bank_mask:0xf
	v_fmac_f32_dpp v45, v45, v44 row_shr:8 row_mask:0xf bank_mask:0xf
	v_mul_f32_dpp v54, v54, v54 row_shr:8 row_mask:0xf bank_mask:0xf
	v_mul_f32_dpp v56, v56, v56 row_shr:8 row_mask:0xf bank_mask:0xf
	v_mul_f32_dpp v42, v42, v42 row_shr:8 row_mask:0xf bank_mask:0xf
	v_mul_f32_dpp v44, v44, v44 row_shr:8 row_mask:0xf bank_mask:0xf
	v_fmac_f32_dpp v55, v55, v54 row_bcast:15 row_mask:0xa bank_mask:0xf
	v_fmac_f32_dpp v57, v57, v56 row_bcast:15 row_mask:0xa bank_mask:0xf
	v_fmac_f32_dpp v43, v43, v42 row_bcast:15 row_mask:0xa bank_mask:0xf
	v_fmac_f32_dpp v45, v45, v44 row_bcast:15 row_mask:0xa bank_mask:0xf
	v_mul_f32_dpp v54, v54, v54 row_bcast:15 row_mask:0xa bank_mask:0xf
	v_mul_f32_dpp v56, v56, v56 row_bcast:15 row_mask:0xa bank_mask:0xf
	v_mul_f32_dpp v42, v42, v42 row_bcast:15 row_mask:0xa bank_mask:0xf
	v_mul_f32_dpp v44, v44, v44 row_bcast:15 row_mask:0xa bank_mask:0xf

; template <int PASS>
; __device__ __forceinline__ void lru_unit(const LruPtrs& args, LAS unsigned char* lds, int chunk, int bl, int g, int ck) {
;     ...
;     if (PASS == 1) {
; #pragma unroll
;     for (int q = 0; q < 8; ++q)
;         asm volatile("s_nop 1\n\t"
;             LRU_STEP("row_shr:1 row_mask:0xf bank_mask:0xf") LRU_STEP("row_shr:2 row_mask:0xf bank_mask:0xf") LRU_STEP("row_shr:4 row_mask:0xf bank_mask:0xf")
;             LRU_STEP("row_shr:8 row_mask:0xf bank_mask:0xf") LRU_STEP("row_bcast:15 row_mask:0xa bank_mask:0xf")
;             : "+v"(uv[q][0]), "+v"(av[q][0]), "+v"(uv[q][1]), "+v"(av[q][1]), "+v"(uv[q][2]), "+v"(av[q][2]), "+v"(uv[q][3]), "+v"(av[q][3]));
	s_nop 1
	v_fmac_f32_dpp v59, v59, v58 row_shr:1 row_mask:0xf bank_mask:0xf
	v_fmac_f32_dpp v61, v61, v60 row_shr:1 row_mask:0xf bank_mask:0xf
	v_fmac_f32_dpp v47, v47, v46 row_shr:1 row_mask:0xf bank_mask:0xf
	v_fmac_f32_dpp v49, v49, v48 row_shr:1 row_mask:0xf bank_mask:0xf
	v_mul_f32_dpp v58, v58, v58 row_shr:1 row_mask:0xf bank_mask:0xf
	v_mul_f32_dpp v60, v60, v60 row_shr:1 row_mask:0xf bank_mask:0xf
	v_mul_f32_dpp v46, v46, v46 row_shr:1 row_mask:0xf bank_mask:0xf
	v_mul_f32_dpp v48, v48, v48 row_shr:1 row_mask:0xf bank_mask:0xf
	v_fmac_f32_dpp v59, v59, v58 row_shr:2 row_mask:0xf bank_mask:0xf
	v_fmac_f32_dpp v61, v61, v60 row_shr:2 row_mask:0xf bank_mask:0xf
	v_fmac_f32_dpp v47, v47, v46 row_shr:2 row_mask:0xf bank_mask:0xf
	v_fmac_f32_dpp v49, v49, v48 row_shr:2 row_mask:0xf bank_mask:0xf
	v_mul_f32_dpp v58, v58, v58 row_shr:2 row_mask:0xf bank_mask:0xf
	v_mul_f32_dpp v60, v60, v60 row_shr:2 row_mask:0xf bank_mask:0xf
	v_mul_f32_dpp v46, v46, v46 row_shr:2 row_mask:0xf bank_mask:0xf
	v_mul_f32_dpp v48, v48, v48 row_shr:2 row_mask:0xf bank_mask:0xf
	v_fmac_f32_dpp v59, v59, v58 row_shr:4 row_mask:0xf bank_mask:0xf
	v_fmac_f32_dpp v61, v61, v60 row_shr:4 row_mask:0xf bank_mask:0xf
	v_fmac_f32_dpp v47, v47, v46 row_shr:4 row_mask:0xf bank_mask:0xf
	v_fmac_f32_dpp v49, v49, v48 row_shr:4 row_mask:0xf bank_mask:0xf
	v_mul_f32_dpp v58, v58, v58 row_shr:4 row_mask:0xf bank_mask:0xf
	v_mul_f32_dpp v60, v60, v60 row_shr:4 row_mask:0xf bank_mask:0xf
	v_mul_f32_dpp v46, v46, v46 row_shr:4 row_mask:0xf bank_mask:0xf
	v_mul_f32_dpp v48, v48, v48 row_shr:4 row_mask:0xf bank_mask:0xf
	v_fmac_f32_dpp v59, v59, v58 row_shr:8 row_mask:0xf bank_mask:0xf
	v_fmac_f32_dpp v61, v61, v60 row_shr:8 row_mask:0xf bank_mask:0xf
	v_fmac_f32_dpp v47, v47, v46 row_shr:8 row_mask:0xf bank_mask:0xf
	v_fmac_f32_dpp v49, v49, v48 row_shr:8 row_mask:0xf bank_mask:0xf
	v_mul_f32_dpp v58, v58, v58 row_shr:8 row_mask:0xf bank_mask:0xf
	v_mul_f32_dpp v60, v60, v60 row_shr:8 row_mask:0xf bank_mask:0xf
	v_mul_f32_dpp v46, v46, v46 row_shr:8 row_mask:0xf bank_mask:0xf
	v_mul_f32_dpp v48, v48, v48 row_shr:8 row_mask:0xf bank_mask:0xf
	v_fmac_f32_dpp v59, v59, v58 row_bcast:15 row_mask:0xa bank_mask:0xf
	v_fmac_f32_dpp v61, v61, v60 row_bcast:15 row_mask:0xa bank_mask:0xf
	v_fmac_f32_dpp v47, v47, v46 row_bcast:15 row_mask:0xa bank_mask:0xf
	v_fmac_f32_dpp v49, v49, v48 row_bcast:15 row_mask:0xa bank_mask:0xf
	v_mul_f32_dpp v58, v58, v58 row_bcast:15 row_mask:0xa bank_mask:0xf
	v_mul_f32_dpp v60, v60, v60 row_bcast:15 row_mask:0xa bank_mask:0xf
	v_mul_f32_dpp v46, v46, v46 row_bcast:15 row_mask:0xa bank_mask:0xf
	v_mul_f32_dpp v48, v48, v48 row_bcast:15 row_mask:0xa bank_mask:0xf

; template <int PASS>
; __device__ __forceinline__ void lru_unit(const LruPtrs& args, LAS unsigned char* lds, int chunk, int bl, int g, int ck) {
;     ...
;     if (PASS == 1) {
; #pragma unroll
;     for (int q = 0; q < 8; ++q)
;         asm volatile("s_nop 1\n\t"
;             LRU_STEP("row_shr:1 row_mask:0xf bank_mask:0xf") LRU_STEP("row_shr:2 row_mask:0xf bank_mask:0xf") LRU_STEP("row_shr:4 row_mask:0xf bank_mask:0xf")
;             LRU_STEP("row_shr:8 row_mask:0xf bank_mask:0xf") LRU_STEP("row_bcast:15 row_mask:0xa bank_mask:0xf")
;             : "+v"(uv[q][0]), "+v"(av[q][0]), "+v"(uv[q][1]), "+v"(av[q][1]), "+v"(uv[q][2]), "+v"(av[q][2]), "+v"(uv[q][3]), "+v"(av[q][3]));
	s_nop 1
	v_fmac_f32_dpp v63, v63, v62 row_shr:1 row_mask:0xf bank_mask:0xf
	v_fmac_f32_dpp v65, v65, v64 row_shr:1 row_mask:0xf bank_mask:0xf
	v_fmac_f32_dpp v3, v3, v2 row_shr:1 row_mask:0xf bank_mask:0xf
	v_fmac_f32_dpp v5, v5, v4 row_shr:1 row_mask:0xf bank_mask:0xf
	v_mul_f32_dpp v62, v62, v62 row_shr:1 row_mask:0xf bank_mask:0xf
	v_mul_f32_dpp v64, v64, v64 row_shr:1 row_mask:0xf bank_mask:0xf
	v_mul_f32_dpp v2, v2, v2 row_shr:1 row_mask:0xf bank_mask:0xf
	v_mul_f32_dpp v4, v4, v4 row_shr:1 row_mask:0xf bank_mask:0xf
	v_fmac_f32_dpp v63, v63, v62 row_shr:2 row_mask:0xf bank_mask:0xf
	v_fmac_f32_dpp v65, v65, v64 row_shr:2 row_mask:0xf bank_mask:0xf
	v_fmac_f32_dpp v3, v3, v2 row_shr:2 row_mask:0xf bank_mask:0xf
	v_fmac_f32_dpp v5, v5, v4 row_shr:2 row_mask:0xf bank_mask:0xf
	v_mul_f32_dpp v62, v62, v62 row_shr:2 row_mask:0xf bank_mask:0xf
	v_mul_f32_dpp v64, v64, v64 row_shr:2 row_mask:0xf bank_mask:0xf
	v_mul_f32_dpp v2, v2, v2 row_shr:2 row_mask:0xf bank_mask:0xf
	v_mul_f32_dpp v4, v4, v4 row_shr:2 row_mask:0xf bank_mask:0xf
	v_fmac_f32_dpp v63, v63, v62 row_shr:4 row_mask:0xf bank_mask:0xf
	v_fmac_f32_dpp v65, v65, v64 row_shr:4 row_mask:0xf bank_mask:0xf
	v_fmac_f32_dpp v3, v3, v2 row_shr:4 row_mask:0xf bank_mask:0xf
	v_fmac_f32_dpp v5, v5, v4 row_shr:4 row_mask:0xf bank_mask:0xf
	v_mul_f32_dpp v62, v62, v62 row_shr:4 row_mask:0xf bank_mask:0xf
	v_mul_f32_dpp v64, v64, v64 row_shr:4 row_mask:0xf bank_mask:0xf
	v_mul_f32_dpp v2, v2, v2 row_shr:4 row_mask:0xf bank_mask:0xf
	v_mul_f32_dpp v4, v4, v4 row_shr:4 row_mask:0xf bank_mask:0xf
	v_fmac_f32_dpp v63, v63, v62 row_shr:8 row_mask:0xf bank_mask:0xf
	v_fmac_f32_dpp v65, v65, v64 row_shr:8 row_mask:0xf bank_mask:0xf
	v_fmac_f32_dpp v3, v3, v2 row_shr:8 row_mask:0xf bank_mask:0xf
	v_fmac_f32_dpp v5, v5, v4 row_shr:8 row_mask:0xf bank_mask:0xf
	v_mul_f32_dpp v62, v62, v62 row_shr:8 row_mask:0xf bank_mask:0xf
	v_mul_f32_dpp v64, v64, v64 row_shr:8 row_mask:0xf bank_mask:0xf
	v_mul_f32_dpp v2, v2, v2 row_shr:8 row_mask:0xf bank_mask:0xf
	v_mul_f32_dpp v4, v4, v4 row_shr:8 row_mask:0xf bank_mask:0xf
	v_fmac_f32_dpp v63, v63, v62 row_bcast:15 row_mask:0xa bank_mask:0xf
	v_fmac_f32_dpp v65, v65, v64 row_bcast:15 row_mask:0xa bank_mask:0xf
	v_fmac_f32_dpp v3, v3, v2 row_bcast:15 row_mask:0xa bank_mask:0xf
	v_fmac_f32_dpp v5, v5, v4 row_bcast:15 row_mask:0xa bank_mask:0xf
	v_mul_f32_dpp v62, v62, v62 row_bcast:15 row_mask:0xa bank_mask:0xf
	v_mul_f32_dpp v64, v64, v64 row_bcast:15 row_mask:0xa bank_mask:0xf
	v_mul_f32_dpp v2, v2, v2 row_bcast:15 row_mask:0xa bank_mask:0xf
	v_mul_f32_dpp v4, v4, v4 row_bcast:15 row_mask:0xa bank_mask:0xf

; template <int PASS>
; __device__ __forceinline__ void lru_unit(const LruPtrs& args, LAS unsigned char* lds, int chunk, int bl, int g, int ck) {
;     ...
;     if (PASS == 1) {
; #pragma unroll
;     for (int q = 0; q < 8; ++q)
;         asm volatile("s_nop 1\n\t"
;             LRU_STEP("row_shr:1 row_mask:0xf bank_mask:0xf") LRU_STEP("row_shr:2 row_mask:0xf bank_mask:0xf") LRU_STEP("row_shr:4 row_mask:0xf bank_mask:0xf")
;             LRU_STEP("row_shr:8 row_mask:0xf bank_mask:0xf") LRU_STEP("row_bcast:15 row_mask:0xa bank_mask:0xf")
;             : "+v"(uv[q][0]), "+v"(av[q][0]), "+v"(uv[q][1]), "+v"(av[q][1]), "+v"(uv[q][2]), "+v"(av[q][2]), "+v"(uv[q][3]), "+v"(av[q][3]));
	s_nop 1
	v_fmac_f32_dpp v19, v19, v18 row_shr:1 row_mask:0xf bank_mask:0xf
	v_fmac_f32_dpp v21, v21, v20 row_shr:1 row_mask:0xf bank_mask:0xf
	v_fmac_f32_dpp v7, v7, v6 row_shr:1 row_mask:0xf bank_mask:0xf
	v_fmac_f32_dpp v9, v9, v8 row_shr:1 row_mask:0xf bank_mask:0xf
	v_mul_f32_dpp v18, v18, v18 row_shr:1 row_mask:0xf bank_mask:0xf
	v_mul_f32_dpp v20, v20, v20 row_shr:1 row_mask:0xf bank_mask:0xf
	v_mul_f32_dpp v6, v6, v6 row_shr:1 row_mask:0xf bank_mask:0xf
	v_mul_f32_dpp v8, v8, v8 row_shr:1 row_mask:0xf bank_mask:0xf
	v_fmac_f32_dpp v19, v19, v18 row_shr:2 row_mask:0xf bank_mask:0xf
	v_fmac_f32_dpp v21, v21, v20 row_shr:2 row_mask:0xf bank_mask:0xf
	v_fmac_f32_dpp v7, v7, v6 row_shr:2 row_mask:0xf bank_mask:0xf
	v_fmac_f32_dpp v9, v9, v8 row_shr:2 row_mask:0xf bank_mask:0xf
	v_mul_f32_dpp v18, v18, v18 row_shr:2 row_mask:0xf bank_mask:0xf
	v_mul_f32_dpp v20, v20, v20 row_shr:2 row_mask:0xf bank_mask:0xf
	v_mul_f32_dpp v6, v6, v6 row_shr:2 row_mask:0xf bank_mask:0xf
	v_mul_f32_dpp v8, v8, v8 row_shr:2 row_mask:0xf bank_mask:0xf
	v_fmac_f32_dpp v19, v19, v18 row_shr:4 row_mask:0xf bank_mask:0xf
	v_fmac_f32_dpp v21, v21, v20 row_shr:4 row_mask:0xf bank_mask:0xf
	v_fmac_f32_dpp v7, v7, v6 row_shr:4 row_mask:0xf bank_mask:0xf
	v_fmac_f32_dpp v9, v9, v8 row_shr:4 row_mask:0xf bank_mask:0xf
	v_mul_f32_dpp v18, v18, v18 row_shr:4 row_mask:0xf bank_mask:0xf
	v_mul_f32_dpp v20, v20, v20 row_shr:4 row_mask:0xf bank_mask:0xf
	v_mul_f32_dpp v6, v6, v6 row_shr:4 row_mask:0xf bank_mask:0xf
	v_mul_f32_dpp v8, v8, v8 row_shr:4 row_mask:0xf bank_mask:0xf
	v_fmac_f32_dpp v19, v19, v18 row_shr:8 row_mask:0xf bank_mask:0xf
	v_fmac_f32_dpp v21, v21, v20 row_shr:8 row_mask:0xf bank_mask:0xf
	v_fmac_f32_dpp v7, v7, v6 row_shr:8 row_mask:0xf bank_mask:0xf
	v_fmac_f32_dpp v9, v9, v8 row_shr:8 row_mask:0xf bank_mask:0xf
	v_mul_f32_dpp v18, v18, v18 row_shr:8 row_mask:0xf bank_mask:0xf
	v_mul_f32_dpp v20, v20, v20 row_shr:8 row_mask:0xf bank_mask:0xf
	v_mul_f32_dpp v6, v6, v6 row_shr:8 row_mask:0xf bank_mask:0xf
	v_mul_f32_dpp v8, v8, v8 row_shr:8 row_mask:0xf bank_mask:0xf
	v_fmac_f32_dpp v19, v19, v18 row_bcast:15 row_mask:0xa bank_mask:0xf
	v_fmac_f32_dpp v21, v21, v20 row_bcast:15 row_mask:0xa bank_mask:0xf
	v_fmac_f32_dpp v7, v7, v6 row_bcast:15 row_mask:0xa bank_mask:0xf
	v_fmac_f32_dpp v9, v9, v8 row_bcast:15 row_mask:0xa bank_mask:0xf
	v_mul_f32_dpp v18, v18, v18 row_bcast:15 row_mask:0xa bank_mask:0xf
	v_mul_f32_dpp v20, v20, v20 row_bcast:15 row_mask:0xa bank_mask:0xf
	v_mul_f32_dpp v6, v6, v6 row_bcast:15 row_mask:0xa bank_mask:0xf
	v_mul_f32_dpp v8, v8, v8 row_bcast:15 row_mask:0xa bank_mask:0xf

; template <int PASS>
; __device__ __forceinline__ void lru_unit(const LruPtrs& args, LAS unsigned char* lds, int chunk, int bl, int g, int ck) {
;     ...
;     if (PASS == 1) {
; #pragma unroll
;     for (int q = 0; q < 8; ++q)
;         asm volatile("s_nop 1\n\t"
;             LRU_STEP("row_shr:1 row_mask:0xf bank_mask:0xf") LRU_STEP("row_shr:2 row_mask:0xf bank_mask:0xf") LRU_STEP("row_shr:4 row_mask:0xf bank_mask:0xf")
;             LRU_STEP("row_shr:8 row_mask:0xf bank_mask:0xf") LRU_STEP("row_bcast:15 row_mask:0xa bank_mask:0xf")
;             : "+v"(uv[q][0]), "+v"(av[q][0]), "+v"(uv[q][1]), "+v"(av[q][1]), "+v"(uv[q][2]), "+v"(av[q][2]), "+v"(uv[q][3]), "+v"(av[q][3]));
	s_nop 1
	v_fmac_f32_dpp v23, v23, v22 row_shr:1 row_mask:0xf bank_mask:0xf
	v_fmac_f32_dpp v25, v25, v24 row_shr:1 row_mask:0xf bank_mask:0xf
	v_fmac_f32_dpp v11, v11, v10 row_shr:1 row_mask:0xf bank_mask:0xf
	v_fmac_f32_dpp v13, v13, v12 row_shr:1 row_mask:0xf bank_mask:0xf
	v_mul_f32_dpp v22, v22, v22 row_shr:1 row_mask:0xf bank_mask:0xf
	v_mul_f32_dpp v24, v24, v24 row_shr:1 row_mask:0xf bank_mask:0xf
	v_mul_f32_dpp v10, v10, v10 row_shr:1 row_mask:0xf bank_mask:0xf
	v_mul_f32_dpp v12, v12, v12 row_shr:1 row_mask:0xf bank_mask:0xf
	v_fmac_f32_dpp v23, v23, v22 row_shr:2 row_mask:0xf bank_mask:0xf
	v_fmac_f32_dpp v25, v25, v24 row_shr:2 row_mask:0xf bank_mask:0xf
	v_fmac_f32_dpp v11, v11, v10 row_shr:2 row_mask:0xf bank_mask:0xf
	v_fmac_f32_dpp v13, v13, v12 row_shr:2 row_mask:0xf bank_mask:0xf
	v_mul_f32_dpp v22, v22, v22 row_shr:2 row_mask:0xf bank_mask:0xf
	v_mul_f32_dpp v24, v24, v24 row_shr:2 row_mask:0xf bank_mask:0xf
	v_mul_f32_dpp v10, v10, v10 row_shr:2 row_mask:0xf bank_mask:0xf
	v_mul_f32_dpp v12, v12, v12 row_shr:2 row_mask:0xf bank_mask:0xf
	v_fmac_f32_dpp v23, v23, v22 row_shr:4 row_mask:0xf bank_mask:0xf
	v_fmac_f32_dpp v25, v25, v24 row_shr:4 row_mask:0xf bank_mask:0xf
	v_fmac_f32_dpp v11, v11, v10 row_shr:4 row_mask:0xf bank_mask:0xf
	v_fmac_f32_dpp v13, v13, v12 row_shr:4 row_mask:0xf bank_mask:0xf
	v_mul_f32_dpp v22, v22, v22 row_shr:4 row_mask:0xf bank_mask:0xf
	v_mul_f32_dpp v24, v24, v24 row_shr:4 row_mask:0xf bank_mask:0xf
	v_mul_f32_dpp v10, v10, v10 row_shr:4 row_mask:0xf bank_mask:0xf
	v_mul_f32_dpp v12, v12, v12 row_shr:4 row_mask:0xf bank_mask:0xf
	v_fmac_f32_dpp v23, v23, v22 row_shr:8 row_mask:0xf bank_mask:0xf
	v_fmac_f32_dpp v25, v25, v24 row_shr:8 row_mask:0xf bank_mask:0xf
	v_fmac_f32_dpp v11, v11, v10 row_shr:8 row_mask:0xf bank_mask:0xf
	v_fmac_f32_dpp v13, v13, v12 row_shr:8 row_mask:0xf bank_mask:0xf
	v_mul_f32_dpp v22, v22, v22 row_shr:8 row_mask:0xf bank_mask:0xf
	v_mul_f32_dpp v24, v24, v24 row_shr:8 row_mask:0xf bank_mask:0xf
	v_mul_f32_dpp v10, v10, v10 row_shr:8 row_mask:0xf bank_mask:0xf
	v_mul_f32_dpp v12, v12, v12 row_shr:8 row_mask:0xf bank_mask:0xf
	v_fmac_f32_dpp v23, v23, v22 row_bcast:15 row_mask:0xa bank_mask:0xf
	v_fmac_f32_dpp v25, v25, v24 row_bcast:15 row_mask:0xa bank_mask:0xf
	v_fmac_f32_dpp v11, v11, v10 row_bcast:15 row_mask:0xa bank_mask:0xf
	v_fmac_f32_dpp v13, v13, v12 row_bcast:15 row_mask:0xa bank_mask:0xf
	v_mul_f32_dpp v22, v22, v22 row_bcast:15 row_mask:0xa bank_mask:0xf
	v_mul_f32_dpp v24, v24, v24 row_bcast:15 row_mask:0xa bank_mask:0xf
	v_mul_f32_dpp v10, v10, v10 row_bcast:15 row_mask:0xa bank_mask:0xf
	v_mul_f32_dpp v12, v12, v12 row_bcast:15 row_mask:0xa bank_mask:0xf

; template <int PASS>
; __device__ __forceinline__ void lru_unit(const LruPtrs& args, LAS unsigned char* lds, int chunk, int bl, int g, int ck) {
;     ...
;     if (PASS == 1) {
; #pragma unroll
;     for (int q = 0; q < 8; ++q)
;         asm volatile("s_nop 1\n\t"
;             LRU_STEP("row_shr:1 row_mask:0xf bank_mask:0xf") LRU_STEP("row_shr:2 row_mask:0xf bank_mask:0xf") LRU_STEP("row_shr:4 row_mask:0xf bank_mask:0xf")
;             LRU_STEP("row_shr:8 row_mask:0xf bank_mask:0xf") LRU_STEP("row_bcast:15 row_mask:0xa bank_mask:0xf")
;             : "+v"(uv[q][0]), "+v"(av[q][0]), "+v"(uv[q][1]), "+v"(av[q][1]), "+v"(uv[q][2]), "+v"(av[q][2]), "+v"(uv[q][3]), "+v"(av[q][3]));
	s_nop 1
	v_fmac_f32_dpp v27, v27, v26 row_shr:1 row_mask:0xf bank_mask:0xf
	v_fmac_f32_dpp v29, v29, v28 row_shr:1 row_mask:0xf bank_mask:0xf
	v_fmac_f32_dpp v15, v15, v14 row_shr:1 row_mask:0xf bank_mask:0xf
	v_fmac_f32_dpp v17, v17, v16 row_shr:1 row_mask:0xf bank_mask:0xf
	v_mul_f32_dpp v26, v26, v26 row_shr:1 row_mask:0xf bank_mask:0xf
	v_mul_f32_dpp v28, v28, v28 row_shr:1 row_mask:0xf bank_mask:0xf
	v_mul_f32_dpp v14, v14, v14 row_shr:1 row_mask:0xf bank_mask:0xf
	v_mul_f32_dpp v16, v16, v16 row_shr:1 row_mask:0xf bank_mask:0xf
	v_fmac_f32_dpp v27, v27, v26 row_shr:2 row_mask:0xf bank_mask:0xf
	v_fmac_f32_dpp v29, v29, v28 row_shr:2 row_mask:0xf bank_mask:0xf
	v_fmac_f32_dpp v15, v15, v14 row_shr:2 row_mask:0xf bank_mask:0xf
	v_fmac_f32_dpp v17, v17, v16 row_shr:2 row_mask:0xf bank_mask:0xf
	v_mul_f32_dpp v26, v26, v26 row_shr:2 row_mask:0xf bank_mask:0xf
	v_mul_f32_dpp v28, v28, v28 row_shr:2 row_mask:0xf bank_mask:0xf
	v_mul_f32_dpp v14, v14, v14 row_shr:2 row_mask:0xf bank_mask:0xf
	v_mul_f32_dpp v16, v16, v16 row_shr:2 row_mask:0xf bank_mask:0xf
	v_fmac_f32_dpp v27, v27, v26 row_shr:4 row_mask:0xf bank_mask:0xf
	v_fmac_f32_dpp v29, v29, v28 row_shr:4 row_mask:0xf bank_mask:0xf
	v_fmac_f32_dpp v15, v15, v14 row_shr:4 row_mask:0xf bank_mask:0xf
	v_fmac_f32_dpp v17, v17, v16 row_shr:4 row_mask:0xf bank_mask:0xf
	v_mul_f32_dpp v26, v26, v26 row_shr:4 row_mask:0xf bank_mask:0xf
	v_mul_f32_dpp v28, v28, v28 row_shr:4 row_mask:0xf bank_mask:0xf
	v_mul_f32_dpp v14, v14, v14 row_shr:4 row_mask:0xf bank_mask:0xf
	v_mul_f32_dpp v16, v16, v16 row_shr:4 row_mask:0xf bank_mask:0xf
	v_fmac_f32_dpp v27, v27, v26 row_shr:8 row_mask:0xf bank_mask:0xf
	v_fmac_f32_dpp v29, v29, v28 row_shr:8 row_mask:0xf bank_mask:0xf
	v_fmac_f32_dpp v15, v15, v14 row_shr:8 row_mask:0xf bank_mask:0xf
	v_fmac_f32_dpp v17, v17, v16 row_shr:8 row_mask:0xf bank_mask:0xf
	v_mul_f32_dpp v26, v26, v26 row_shr:8 row_mask:0xf bank_mask:0xf
	v_mul_f32_dpp v28, v28, v28 row_shr:8 row_mask:0xf bank_mask:0xf
	v_mul_f32_dpp v14, v14, v14 row_shr:8 row_mask:0xf bank_mask:0xf
	v_mul_f32_dpp v16, v16, v16 row_shr:8 row_mask:0xf bank_mask:0xf
	v_fmac_f32_dpp v27, v27, v26 row_bcast:15 row_mask:0xa bank_mask:0xf
	v_fmac_f32_dpp v29, v29, v28 row_bcast:15 row_mask:0xa bank_mask:0xf
	v_fmac_f32_dpp v15, v15, v14 row_bcast:15 row_mask:0xa bank_mask:0xf
	v_fmac_f32_dpp v17, v17, v16 row_bcast:15 row_mask:0xa bank_mask:0xf
	v_mul_f32_dpp v26, v26, v26 row_bcast:15 row_mask:0xa bank_mask:0xf
	v_mul_f32_dpp v28, v28, v28 row_bcast:15 row_mask:0xa bank_mask:0xf
	v_mul_f32_dpp v14, v14, v14 row_bcast:15 row_mask:0xa bank_mask:0xf
	v_mul_f32_dpp v16, v16, v16 row_bcast:15 row_mask:0xa bank_mask:0xf

; __device__ __forceinline__ unsigned cvt_pk_bf16(float lo, float hi) { unsigned r; asm volatile("v_cvt_pk_bf16_f32 %0, %1, %2" : "=v"(r) : "v"(lo), "v"(hi)); return r; }
; template <int PASS>
; __device__ __forceinline__ void lru_unit(const LruPtrs& args, LAS unsigned char* lds, int chunk, int bl, int g, int ck) {
;     ...
; #pragma unroll
;     for (int q = 0; q < 8; ++q) { v4u st;
; #pragma unroll
;         for (int p = 0; p < 4; ++p) st[p] = pg8::cvt_pk_bf16(av[q][p], uv[q][p]);
;         stash[q * 64] = st; }
;     }
;     ...
;     if (PASS == 1 && n == 31) {
; #pragma unroll
;         for (int q = 0; q < 8; ++q)
; #pragma unroll
;             for (int p = 0; p < 4; ++p) { const int ci = 8 * q + 4 * hi + p; WAG[(w * 64 + ci) * 2] = av[q][p]; WAG[(w * 64 + ci) * 2 + 1] = uv[q][p]; }
;     }
	s_nop 0
	v_cvt_pk_bf16_f32 v30, v66, v67
	v_cvt_pk_bf16_f32 v31, v68, v69
	v_cvt_pk_bf16_f32 v32, v34, v35
	v_cvt_pk_bf16_f32 v33, v36, v37
	s_nop 0
	v_addc_co_u32_e32 v73, vcc, 0, v73, vcc
	global_store_dwordx4 v[72:73], v[30:33], off offset:-4096
	v_cmp_eq_u32_e32 vcc, 31, v87
	s_nop 0
	v_cvt_pk_bf16_f32 v30, v50, v51
	v_cvt_pk_bf16_f32 v31, v52, v53
	v_cvt_pk_bf16_f32 v32, v38, v39
	v_cvt_pk_bf16_f32 v33, v40, v41
	global_store_dwordx4 v[70:71], v[30:33], off offset:1024
	s_nop 1
	v_cvt_pk_bf16_f32 v30, v54, v55
	v_cvt_pk_bf16_f32 v31, v56, v57
	v_cvt_pk_bf16_f32 v32, v42, v43
	v_cvt_pk_bf16_f32 v33, v44, v45
	global_store_dwordx4 v[70:71], v[30:33], off offset:2048
	s_nop 1
	v_cvt_pk_bf16_f32 v30, v58, v59
	v_cvt_pk_bf16_f32 v31, v60, v61
	v_cvt_pk_bf16_f32 v32, v46, v47
	v_cvt_pk_bf16_f32 v33, v48, v49
	global_store_dwordx4 v[70:71], v[30:33], off offset:3072
	s_nop 1
	v_cvt_pk_bf16_f32 v30, v62, v63
	v_cvt_pk_bf16_f32 v31, v64, v65
	v_cvt_pk_bf16_f32 v32, v2, v3
	v_cvt_pk_bf16_f32 v33, v4, v5
	global_store_dwordx4 v[72:73], v[30:33], off
	s_nop 1
	v_cvt_pk_bf16_f32 v30, v18, v19
	v_cvt_pk_bf16_f32 v31, v20, v21
	v_cvt_pk_bf16_f32 v32, v6, v7
	v_cvt_pk_bf16_f32 v33, v8, v9
	global_store_dwordx4 v[72:73], v[30:33], off offset:1024
	s_nop 1
	v_cvt_pk_bf16_f32 v30, v22, v23
	v_cvt_pk_bf16_f32 v31, v24, v25
	v_cvt_pk_bf16_f32 v32, v10, v11
	v_cvt_pk_bf16_f32 v33, v12, v13
	global_store_dwordx4 v[72:73], v[30:33], off offset:2048
	s_nop 1
	v_cvt_pk_bf16_f32 v30, v26, v27
	v_cvt_pk_bf16_f32 v31, v28, v29
	v_cvt_pk_bf16_f32 v32, v14, v15
	v_cvt_pk_bf16_f32 v33, v16, v17
	global_store_dwordx4 v[72:73], v[30:33], off offset:3072
	s_and_saveexec_b64 s[4:5], vcc
	s_cbranch_execz .LBB0_447
	v_or_b32_e32 v0, s47, v88
	v_lshl_add_u32 v0, v0, 3, 0
	ds_write_b128 v0, v[66:69]
	ds_write_b128 v0, v[34:37] offset:16
	ds_write_b128 v0, v[50:53] offset:64
	ds_write_b128 v0, v[38:41] offset:80
	ds_write_b128 v0, v[54:57] offset:128
	ds_write_b128 v0, v[42:45] offset:144
	ds_write_b128 v0, v[58:61] offset:192
	ds_write_b128 v0, v[46:49] offset:208
	ds_write_b128 v0, v[62:65] offset:256
	ds_write_b128 v0, v[2:5] offset:272
	ds_write_b128 v0, v[18:21] offset:320
	ds_write_b128 v0, v[6:9] offset:336
	ds_write_b128 v0, v[22:25] offset:384
	ds_write_b128 v0, v[10:13] offset:400
	ds_write_b128 v0, v[26:29] offset:448
	ds_write_b128 v0, v[14:17] offset:464
